# v54 + ph0 weight-conversion items read their 32 LDS transposed pairs in one batch (hoisted ds_read2)
# baseline (speedup 1.0000x reference)
.LBB0_409:
	v_add_u32_e32 v222, 0x400, v80
	ds_read2_b32 v[148:149], v80 offset1:65
	ds_read2_b32 v[150:151], v80 offset0:130 offset1:195
	ds_read2_b32 v[152:153], v222 offset0:4 offset1:69
	ds_read2_b32 v[154:155], v222 offset0:134 offset1:199
	ds_read2_b32 v[156:157], v80 offset0:8 offset1:73
	ds_read2_b32 v[158:159], v80 offset0:138 offset1:203
	ds_read2_b32 v[160:161], v222 offset0:12 offset1:77
	ds_read2_b32 v[162:163], v222 offset0:142 offset1:207
	ds_read2_b32 v[164:165], v80 offset0:16 offset1:81
	ds_read2_b32 v[166:167], v80 offset0:146 offset1:211
	ds_read2_b32 v[168:169], v222 offset0:20 offset1:85
	ds_read2_b32 v[170:171], v222 offset0:150 offset1:215
	ds_read2_b32 v[172:173], v80 offset0:24 offset1:89
	ds_read2_b32 v[174:175], v80 offset0:154 offset1:219
	ds_read2_b32 v[176:177], v222 offset0:28 offset1:93
	ds_read2_b32 v[178:179], v222 offset0:158 offset1:223
	ds_read2_b32 v[180:181], v80 offset0:32 offset1:97
	ds_read2_b32 v[182:183], v80 offset0:162 offset1:227
	ds_read2_b32 v[184:185], v222 offset0:36 offset1:101
	ds_read2_b32 v[186:187], v222 offset0:166 offset1:231
	ds_read2_b32 v[188:189], v80 offset0:40 offset1:105
	ds_read2_b32 v[190:191], v80 offset0:170 offset1:235
	ds_read2_b32 v[192:193], v222 offset0:44 offset1:109
	ds_read2_b32 v[194:195], v222 offset0:174 offset1:239
	ds_read2_b32 v[196:197], v80 offset0:48 offset1:113
	ds_read2_b32 v[198:199], v80 offset0:178 offset1:243
	ds_read2_b32 v[210:211], v222 offset0:52 offset1:117
	ds_read2_b32 v[212:213], v222 offset0:182 offset1:247
	ds_read2_b32 v[214:215], v80 offset0:56 offset1:121
	ds_read2_b32 v[216:217], v80 offset0:186 offset1:251
	ds_read2_b32 v[218:219], v222 offset0:60 offset1:125
	ds_read2_b32 v[220:221], v222 offset0:190 offset1:255
	s_nop 0
	s_sub_i32 s4, 0, s4
	s_add_i32 s4, s4, s22
	v_add_u32_e32 v58, s4, v79
	v_ashrrev_i32_e32 v59, 31, v58
	s_waitcnt vmcnt(1) lgkmcnt(0)
	v_mul_f32_e32 v29, v4, v148
	v_mul_f32_e32 v50, v5, v149
	v_cvt_pk_bf16_f32 v52, v29, v50
	s_nop 0
	v_add_u32_e32 v29, 0x400, v80
	v_lshlrev_b64 v[60:61], 12, v[58:59]
	s_waitcnt lgkmcnt(0)
	v_mul_f32_e32 v50, v6, v150
	v_mul_f32_e32 v51, v7, v151
	v_cvt_pk_bf16_f32 v53, v50, v51
	s_nop 0
	s_waitcnt vmcnt(0) lgkmcnt(0)
	v_mul_f32_e32 v50, v0, v152
	v_mul_f32_e32 v51, v1, v153
	v_cvt_pk_bf16_f32 v54, v50, v51
	s_nop 0
	v_lshl_add_u64 v[50:51], s[0:1], 1, v[48:49]
	v_lshl_add_u64 v[60:61], v[50:51], 0, v[60:61]
	s_waitcnt lgkmcnt(0)
	v_mul_f32_e32 v55, v2, v154
	v_mul_f32_e32 v56, v3, v155
	v_cvt_pk_bf16_f32 v55, v55, v56
	s_nop 0
	global_store_dwordx4 v[60:61], v[52:55], off
	v_add_u32_e32 v60, 8, v58
	v_ashrrev_i32_e32 v61, 31, v60
	v_lshlrev_b64 v[60:61], 12, v[60:61]
	s_waitcnt lgkmcnt(0)
	v_mul_f32_e32 v52, v4, v156
	v_mul_f32_e32 v53, v5, v157
	v_cvt_pk_bf16_f32 v52, v52, v53
	s_nop 0
	v_lshl_add_u64 v[60:61], v[50:51], 0, v[60:61]
	s_waitcnt lgkmcnt(0)
	v_mul_f32_e32 v53, v6, v158
	v_mul_f32_e32 v54, v7, v159
	v_cvt_pk_bf16_f32 v53, v53, v54
	s_nop 0
	s_waitcnt lgkmcnt(0)
	v_mul_f32_e32 v54, v0, v160
	v_mul_f32_e32 v55, v1, v161
	v_cvt_pk_bf16_f32 v54, v54, v55
	s_nop 0
	s_waitcnt lgkmcnt(0)
	v_mul_f32_e32 v55, v2, v162
	v_mul_f32_e32 v56, v3, v163
	v_cvt_pk_bf16_f32 v55, v55, v56
	s_nop 0
	global_store_dwordx4 v[60:61], v[52:55], off
	v_add_u32_e32 v60, 16, v58
	v_ashrrev_i32_e32 v61, 31, v60
	v_lshlrev_b64 v[60:61], 12, v[60:61]
	s_waitcnt lgkmcnt(0)
	v_mul_f32_e32 v52, v4, v164
	v_mul_f32_e32 v53, v5, v165
	v_cvt_pk_bf16_f32 v52, v52, v53
	s_nop 0
	v_lshl_add_u64 v[60:61], v[50:51], 0, v[60:61]
	s_waitcnt lgkmcnt(0)
	v_mul_f32_e32 v53, v6, v166
	v_mul_f32_e32 v54, v7, v167
	v_cvt_pk_bf16_f32 v53, v53, v54
	s_nop 0
	s_waitcnt lgkmcnt(0)
	v_mul_f32_e32 v54, v0, v168
	v_mul_f32_e32 v55, v1, v169
	v_cvt_pk_bf16_f32 v54, v54, v55
	s_nop 0
	s_waitcnt lgkmcnt(0)
	v_mul_f32_e32 v55, v2, v170
	v_mul_f32_e32 v56, v3, v171
	v_cvt_pk_bf16_f32 v55, v55, v56
	s_nop 0
	global_store_dwordx4 v[60:61], v[52:55], off
	v_add_u32_e32 v60, 24, v58
	v_ashrrev_i32_e32 v61, 31, v60
	v_lshlrev_b64 v[60:61], 12, v[60:61]
	s_waitcnt lgkmcnt(0)
	v_mul_f32_e32 v52, v4, v172
	v_mul_f32_e32 v53, v5, v173
	v_cvt_pk_bf16_f32 v52, v52, v53
	s_nop 0
	v_lshl_add_u64 v[60:61], v[50:51], 0, v[60:61]
	s_waitcnt lgkmcnt(0)
	v_mul_f32_e32 v53, v6, v174
	v_mul_f32_e32 v54, v7, v175
	v_cvt_pk_bf16_f32 v53, v53, v54
	s_nop 0
	s_waitcnt lgkmcnt(0)
	v_mul_f32_e32 v54, v0, v176
	v_mul_f32_e32 v55, v1, v177
	v_cvt_pk_bf16_f32 v54, v54, v55
	s_nop 0
	s_waitcnt lgkmcnt(0)
	v_mul_f32_e32 v55, v2, v178
	v_mul_f32_e32 v56, v3, v179
	v_cvt_pk_bf16_f32 v55, v55, v56
	s_nop 0
	global_store_dwordx4 v[60:61], v[52:55], off
	v_add_u32_e32 v60, 32, v58
	v_ashrrev_i32_e32 v61, 31, v60
	v_lshlrev_b64 v[60:61], 12, v[60:61]
	s_waitcnt lgkmcnt(0)
	v_mul_f32_e32 v52, v4, v180
	v_mul_f32_e32 v53, v5, v181
	v_cvt_pk_bf16_f32 v52, v52, v53
	s_nop 0
	v_lshl_add_u64 v[60:61], v[50:51], 0, v[60:61]
	s_waitcnt lgkmcnt(0)
	v_mul_f32_e32 v53, v6, v182
	v_mul_f32_e32 v54, v7, v183
	v_cvt_pk_bf16_f32 v53, v53, v54
	s_nop 0
	s_waitcnt lgkmcnt(0)
	v_mul_f32_e32 v54, v0, v184
	v_mul_f32_e32 v55, v1, v185
	v_cvt_pk_bf16_f32 v54, v54, v55
	s_nop 0
	s_waitcnt lgkmcnt(0)
	v_mul_f32_e32 v55, v2, v186
	v_mul_f32_e32 v56, v3, v187
	v_cvt_pk_bf16_f32 v55, v55, v56
	s_nop 0
	global_store_dwordx4 v[60:61], v[52:55], off
	v_add_u32_e32 v60, 40, v58
	v_ashrrev_i32_e32 v61, 31, v60
	v_lshlrev_b64 v[60:61], 12, v[60:61]
	s_waitcnt lgkmcnt(0)
	v_mul_f32_e32 v52, v4, v188
	v_mul_f32_e32 v53, v5, v189
	v_cvt_pk_bf16_f32 v52, v52, v53
	s_nop 0
	v_lshl_add_u64 v[60:61], v[50:51], 0, v[60:61]
	s_waitcnt lgkmcnt(0)
	v_mul_f32_e32 v53, v6, v190
	v_mul_f32_e32 v54, v7, v191
	v_cvt_pk_bf16_f32 v53, v53, v54
	s_nop 0
	s_waitcnt lgkmcnt(0)
	v_mul_f32_e32 v54, v0, v192
	v_mul_f32_e32 v55, v1, v193
	v_cvt_pk_bf16_f32 v54, v54, v55
	s_nop 0
	s_waitcnt lgkmcnt(0)
	v_mul_f32_e32 v55, v2, v194
	v_mul_f32_e32 v56, v3, v195
	v_cvt_pk_bf16_f32 v55, v55, v56
	s_nop 0
	global_store_dwordx4 v[60:61], v[52:55], off
	v_add_u32_e32 v60, 48, v58
	v_ashrrev_i32_e32 v61, 31, v60
	v_lshlrev_b64 v[60:61], 12, v[60:61]
	s_waitcnt lgkmcnt(0)
	v_mul_f32_e32 v52, v4, v196
	v_mul_f32_e32 v53, v5, v197
	v_cvt_pk_bf16_f32 v52, v52, v53
	s_nop 0
	v_lshl_add_u64 v[60:61], v[50:51], 0, v[60:61]
	s_waitcnt lgkmcnt(0)
	v_mul_f32_e32 v53, v6, v198
	v_mul_f32_e32 v54, v7, v199
	v_cvt_pk_bf16_f32 v53, v53, v54
	s_nop 0
	s_waitcnt lgkmcnt(0)
	v_mul_f32_e32 v54, v0, v210
	v_mul_f32_e32 v55, v1, v211
	v_cvt_pk_bf16_f32 v54, v54, v55
	s_nop 0
	s_waitcnt lgkmcnt(0)
	v_mul_f32_e32 v55, v2, v212
	v_mul_f32_e32 v56, v3, v213
	v_cvt_pk_bf16_f32 v55, v55, v56
	s_nop 0
	global_store_dwordx4 v[60:61], v[52:55], off
	s_waitcnt lgkmcnt(0)
	v_mul_f32_e32 v4, v4, v214
	v_mul_f32_e32 v5, v5, v215
	v_cvt_pk_bf16_f32 v4, v4, v5
	s_nop 0
	s_waitcnt lgkmcnt(0)
	v_mul_f32_e32 v5, v6, v216
	v_mul_f32_e32 v6, v7, v217
	v_cvt_pk_bf16_f32 v5, v5, v6
	s_nop 0
	v_add_u32_e32 v52, 56, v58
	v_ashrrev_i32_e32 v53, 31, v52
	v_lshlrev_b64 v[52:53], 12, v[52:53]
	s_waitcnt lgkmcnt(0)
	v_mul_f32_e32 v0, v0, v218
	v_mul_f32_e32 v1, v1, v219
	v_cvt_pk_bf16_f32 v6, v0, v1
	s_nop 0
	s_waitcnt lgkmcnt(0)
	v_mul_f32_e32 v0, v2, v220
	v_mul_f32_e32 v1, v3, v221
	v_cvt_pk_bf16_f32 v7, v0, v1
	v_lshl_add_u64 v[0:1], v[50:51], 0, v[52:53]
	global_store_dwordx4 v[0:1], v[4:7], off
	s_waitcnt lgkmcnt(0)

.LBB0_411:
	s_mov_b64 s[0:1], -1
	s_and_b64 vcc, exec, s[10:11]
	s_cbranch_vccz .LBB0_449
	s_and_b64 vcc, exec, s[14:15]
	s_cbranch_vccz .LBB0_446
	s_and_b64 vcc, exec, s[26:27]
	s_cbranch_vccz .LBB0_440
	s_and_b64 vcc, exec, s[28:29]
	s_cbranch_vccz .LBB0_434
	s_and_b64 vcc, exec, s[16:17]
	s_cbranch_vccz .LBB0_431
	s_and_b64 vcc, exec, s[20:21]
	s_cbranch_vccz .LBB0_425
	s_ashr_i32 s0, s49, 31
	s_lshr_b32 s0, s0, 27
	s_add_i32 s0, s49, s0
	s_ashr_i32 s0, s0, 5
	s_lshl_b32 s1, s0, 11
	s_lshl_b32 s0, s0, 6
	v_or_b32_e32 v0, s0, v11
	v_or_b32_e32 v2, 4, v0
	v_ashrrev_i32_e32 v3, 31, v2
	v_lshlrev_b64 v[70:71], 13, v[2:3]
	v_or_b32_e32 v2, 8, v0
	v_ashrrev_i32_e32 v3, 31, v2
	v_lshlrev_b64 v[58:59], 13, v[2:3]
	v_or_b32_e32 v2, 12, v0
	v_ashrrev_i32_e32 v3, 31, v2
	v_lshlrev_b64 v[60:61], 13, v[2:3]
	v_or_b32_e32 v2, 16, v0
	v_ashrrev_i32_e32 v3, 31, v2
	v_lshlrev_b64 v[62:63], 13, v[2:3]
	v_or_b32_e32 v2, 20, v0
	v_ashrrev_i32_e32 v3, 31, v2
	v_lshlrev_b64 v[64:65], 13, v[2:3]
	v_or_b32_e32 v2, 24, v0
	v_ashrrev_i32_e32 v3, 31, v2
	v_lshlrev_b64 v[66:67], 13, v[2:3]
	v_or_b32_e32 v2, 28, v0
	v_ashrrev_i32_e32 v1, 31, v0
	v_ashrrev_i32_e32 v3, 31, v2
	s_sub_i32 s4, s22, s1
	v_lshlrev_b64 v[72:73], 13, v[0:1]
	v_lshlrev_b64 v[68:69], 13, v[2:3]
	v_or_b32_e32 v56, 32, v0
	v_or_b32_e32 v54, 36, v0
	v_or_b32_e32 v52, 40, v0
	v_or_b32_e32 v50, 44, v0
	v_or_b32_e32 v6, 48, v0
	v_or_b32_e32 v4, 52, v0
	v_or_b32_e32 v2, 56, v0
	v_or_b32_e32 v0, 60, v0
	s_sub_i32 s25, 0, s1
	s_ashr_i32 s5, s4, 31
	s_mov_b64 s[6:7], -1
	s_and_b64 vcc, exec, s[34:35]
	v_ashrrev_i32_e32 v57, 31, v56
	v_ashrrev_i32_e32 v55, 31, v54
	v_ashrrev_i32_e32 v53, 31, v52
	v_ashrrev_i32_e32 v51, 31, v50
	v_ashrrev_i32_e32 v7, 31, v6
	v_ashrrev_i32_e32 v5, 31, v4
	v_ashrrev_i32_e32 v3, 31, v2
	v_ashrrev_i32_e32 v1, 31, v0
	s_cbranch_vccz .LBB0_419
	s_load_dwordx2 s[6:7], s[30:31], 0x70
	v_lshlrev_b32_e32 v204, 2, v8
	v_lshlrev_b64 v[116:117], 13, v[56:57]
	v_lshlrev_b64 v[120:121], 13, v[54:55]
	v_lshlrev_b64 v[124:125], 13, v[52:53]
	s_waitcnt lgkmcnt(0)
	s_add_u32 s1, s6, s36
	s_addc_u32 s61, s7, s37
	s_lshl_b64 s[6:7], s[4:5], 2
	s_add_u32 s6, s1, s6
	s_addc_u32 s7, s61, s7
	v_lshl_add_u64 v[144:145], s[6:7], 0, v[204:205]
	v_lshl_add_u64 v[74:75], v[144:145], 0, v[72:73]
	v_lshl_add_u64 v[88:89], v[144:145], 0, v[70:71]
	global_load_dwordx4 v[74:77], v[74:75], off
	v_lshl_add_u64 v[92:93], v[144:145], 0, v[58:59]
	global_load_dwordx4 v[88:91], v[88:89], off
	v_lshl_add_u64 v[96:97], v[144:145], 0, v[60:61]
	global_load_dwordx4 v[92:95], v[92:93], off
	v_lshl_add_u64 v[100:101], v[144:145], 0, v[62:63]
	global_load_dwordx4 v[96:99], v[96:97], off
	v_lshl_add_u64 v[104:105], v[144:145], 0, v[64:65]
	global_load_dwordx4 v[100:103], v[100:101], off
	v_lshl_add_u64 v[108:109], v[144:145], 0, v[66:67]
	global_load_dwordx4 v[104:107], v[104:105], off
	v_lshl_add_u64 v[112:113], v[144:145], 0, v[68:69]
	global_load_dwordx4 v[108:111], v[108:109], off
	v_lshl_add_u64 v[116:117], v[144:145], 0, v[116:117]
	global_load_dwordx4 v[112:115], v[112:113], off
	v_lshl_add_u64 v[120:121], v[144:145], 0, v[120:121]
	global_load_dwordx4 v[116:119], v[116:117], off
	v_lshl_add_u64 v[124:125], v[144:145], 0, v[124:125]
	global_load_dwordx4 v[120:123], v[120:121], off
	v_lshlrev_b64 v[128:129], 13, v[50:51]
	global_load_dwordx4 v[124:127], v[124:125], off
	v_lshl_add_u64 v[128:129], v[144:145], 0, v[128:129]
	global_load_dwordx4 v[128:131], v[128:129], off
	v_lshlrev_b64 v[132:133], 13, v[6:7]
	v_lshl_add_u64 v[132:133], v[144:145], 0, v[132:133]
	global_load_dwordx4 v[132:135], v[132:133], off
	v_lshlrev_b64 v[136:137], 13, v[4:5]
	v_lshl_add_u64 v[136:137], v[144:145], 0, v[136:137]
	global_load_dwordx4 v[136:139], v[136:137], off
	v_lshlrev_b64 v[140:141], 13, v[2:3]
	v_lshl_add_u64 v[140:141], v[144:145], 0, v[140:141]
	global_load_dwordx4 v[140:143], v[140:141], off
	v_lshlrev_b64 v[146:147], 13, v[0:1]
	v_lshl_add_u64 v[144:145], v[144:145], 0, v[146:147]
	global_load_dwordx4 v[144:147], v[144:145], off
	v_add_u32_e32 v29, 0x410, v78
	s_ashr_i32 s1, s0, 31
	s_mov_b64 s[6:7], 0
	s_waitcnt vmcnt(0)
	ds_write2_b32 v78, v74, v75 offset1:1
	ds_write2_b32 v78, v76, v77 offset0:2 offset1:3
	v_lshl_add_u64 v[74:75], s[0:1], 1, v[26:27]
	ds_write2_b32 v29, v88, v89 offset1:1
	v_add_u32_e32 v29, 0x418, v78
	ds_write2_b32 v29, v90, v91 offset1:1
	v_add_u32_e32 v29, 0x820, v78
	ds_write2_b32 v29, v92, v93 offset1:1
	v_add_u32_e32 v29, 0x828, v78
	ds_write2_b32 v29, v94, v95 offset1:1
	v_add_u32_e32 v29, 0xc30, v78
	ds_write2_b32 v29, v96, v97 offset1:1
	v_add_u32_e32 v29, 0xc38, v78
	ds_write2_b32 v29, v98, v99 offset1:1
	v_add_u32_e32 v29, 0x1040, v78
	ds_write2_b32 v29, v100, v101 offset1:1
	v_add_u32_e32 v29, 0x1048, v78
	ds_write2_b32 v29, v102, v103 offset1:1
	v_add_u32_e32 v29, 0x1450, v78
	ds_write2_b32 v29, v104, v105 offset1:1
	v_add_u32_e32 v29, 0x1458, v78
	ds_write2_b32 v29, v106, v107 offset1:1
	v_add_u32_e32 v29, 0x1860, v78
	ds_write2_b32 v29, v108, v109 offset1:1
	v_add_u32_e32 v29, 0x1868, v78
	ds_write2_b32 v29, v110, v111 offset1:1
	v_add_u32_e32 v29, 0x1c70, v78
	ds_write2_b32 v29, v112, v113 offset1:1
	v_add_u32_e32 v29, 0x1c78, v78
	ds_write2_b32 v29, v114, v115 offset1:1
	v_add_u32_e32 v29, 0x2080, v78
	ds_write2_b32 v29, v116, v117 offset1:1
	v_add_u32_e32 v29, 0x2088, v78
	ds_write2_b32 v29, v118, v119 offset1:1
	v_add_u32_e32 v29, 0x2490, v78
	ds_write2_b32 v29, v120, v121 offset1:1
	v_add_u32_e32 v29, 0x2498, v78
	ds_write2_b32 v29, v122, v123 offset1:1
	v_add_u32_e32 v29, 0x28a0, v78
	ds_write2_b32 v29, v124, v125 offset1:1
	v_add_u32_e32 v29, 0x28a8, v78
	ds_write2_b32 v29, v126, v127 offset1:1
	v_add_u32_e32 v29, 0x2cb0, v78
	ds_write2_b32 v29, v128, v129 offset1:1
	v_add_u32_e32 v29, 0x2cb8, v78
	ds_write2_b32 v29, v130, v131 offset1:1
	v_add_u32_e32 v29, 0x30c0, v78
	ds_write2_b32 v29, v132, v133 offset1:1
	v_add_u32_e32 v29, 0x30c8, v78
	ds_write2_b32 v29, v134, v135 offset1:1
	v_add_u32_e32 v29, 0x34d0, v78
	ds_write2_b32 v29, v136, v137 offset1:1
	v_add_u32_e32 v29, 0x34d8, v78
	ds_write2_b32 v29, v138, v139 offset1:1
	v_add_u32_e32 v29, 0x38e0, v78
	ds_write2_b32 v29, v140, v141 offset1:1
	v_add_u32_e32 v29, 0x38e8, v78
	ds_write2_b32 v29, v142, v143 offset1:1
	v_add_u32_e32 v29, 0x3cf0, v78
	ds_write2_b32 v29, v144, v145 offset1:1
	v_add_u32_e32 v29, 0x3cf8, v78
	ds_write2_b32 v29, v146, v147 offset1:1
	s_waitcnt lgkmcnt(0)
	v_add_u32_e32 v222, 0x400, v80
	ds_read2_b32 v[148:149], v80 offset1:65
	ds_read2_b32 v[150:151], v80 offset0:130 offset1:195
	ds_read2_b32 v[152:153], v222 offset0:4 offset1:69
	ds_read2_b32 v[154:155], v222 offset0:134 offset1:199
	ds_read2_b32 v[156:157], v80 offset0:8 offset1:73
	ds_read2_b32 v[158:159], v80 offset0:138 offset1:203
	ds_read2_b32 v[160:161], v222 offset0:12 offset1:77
	ds_read2_b32 v[162:163], v222 offset0:142 offset1:207
	ds_read2_b32 v[164:165], v80 offset0:16 offset1:81
	ds_read2_b32 v[166:167], v80 offset0:146 offset1:211
	ds_read2_b32 v[168:169], v222 offset0:20 offset1:85
	ds_read2_b32 v[170:171], v222 offset0:150 offset1:215
	ds_read2_b32 v[172:173], v80 offset0:24 offset1:89
	ds_read2_b32 v[174:175], v80 offset0:154 offset1:219
	ds_read2_b32 v[176:177], v222 offset0:28 offset1:93
	ds_read2_b32 v[178:179], v222 offset0:158 offset1:223
	ds_read2_b32 v[180:181], v80 offset0:32 offset1:97
	ds_read2_b32 v[182:183], v80 offset0:162 offset1:227
	ds_read2_b32 v[184:185], v222 offset0:36 offset1:101
	ds_read2_b32 v[186:187], v222 offset0:166 offset1:231
	ds_read2_b32 v[188:189], v80 offset0:40 offset1:105
	ds_read2_b32 v[190:191], v80 offset0:170 offset1:235
	ds_read2_b32 v[192:193], v222 offset0:44 offset1:109
	ds_read2_b32 v[194:195], v222 offset0:174 offset1:239
	ds_read2_b32 v[196:197], v80 offset0:48 offset1:113
	ds_read2_b32 v[198:199], v80 offset0:178 offset1:243
	ds_read2_b32 v[210:211], v222 offset0:52 offset1:117
	ds_read2_b32 v[212:213], v222 offset0:182 offset1:247
	ds_read2_b32 v[214:215], v80 offset0:56 offset1:121
	ds_read2_b32 v[216:217], v80 offset0:186 offset1:251
	ds_read2_b32 v[218:219], v222 offset0:60 offset1:125
	ds_read2_b32 v[220:221], v222 offset0:190 offset1:255
	s_nop 0
	s_waitcnt lgkmcnt(0)
	v_cvt_pk_bf16_f32 v88, v148, v149
	s_nop 0
	v_add_u32_e32 v29, 0x400, v80
	s_waitcnt lgkmcnt(0)
	v_cvt_pk_bf16_f32 v89, v150, v151
	s_nop 0
	s_waitcnt lgkmcnt(0)
	v_cvt_pk_bf16_f32 v90, v152, v153
	s_nop 0
	s_add_i32 s1, s25, s22
	s_waitcnt lgkmcnt(0)
	v_cvt_pk_bf16_f32 v91, v154, v155
	v_add_u32_e32 v76, s1, v79
	v_ashrrev_i32_e32 v77, 31, v76
	v_lshlrev_b64 v[92:93], 12, v[76:77]
	v_lshl_add_u64 v[92:93], v[74:75], 0, v[92:93]
	global_store_dwordx4 v[92:93], v[88:91], off
	s_nop 0
	s_waitcnt lgkmcnt(0)
	v_cvt_pk_bf16_f32 v88, v156, v157
	s_nop 0
	s_waitcnt lgkmcnt(0)
	v_cvt_pk_bf16_f32 v89, v158, v159
	s_nop 0
	s_waitcnt lgkmcnt(0)
	v_cvt_pk_bf16_f32 v90, v160, v161
	s_nop 0
	s_waitcnt lgkmcnt(0)
	v_cvt_pk_bf16_f32 v91, v162, v163
	v_add_u32_e32 v92, 8, v76
	v_ashrrev_i32_e32 v93, 31, v92
	v_lshlrev_b64 v[92:93], 12, v[92:93]
	v_lshl_add_u64 v[92:93], v[74:75], 0, v[92:93]
	global_store_dwordx4 v[92:93], v[88:91], off
	s_nop 0
	s_waitcnt lgkmcnt(0)
	v_cvt_pk_bf16_f32 v88, v164, v165
	s_nop 0
	s_waitcnt lgkmcnt(0)
	v_cvt_pk_bf16_f32 v89, v166, v167
	s_nop 0
	s_waitcnt lgkmcnt(0)
	v_cvt_pk_bf16_f32 v90, v168, v169
	s_nop 0
	s_waitcnt lgkmcnt(0)
	v_cvt_pk_bf16_f32 v91, v170, v171
	v_add_u32_e32 v92, 16, v76
	v_ashrrev_i32_e32 v93, 31, v92
	v_lshlrev_b64 v[92:93], 12, v[92:93]
	v_lshl_add_u64 v[92:93], v[74:75], 0, v[92:93]
	global_store_dwordx4 v[92:93], v[88:91], off
	s_nop 0
	s_waitcnt lgkmcnt(0)
	v_cvt_pk_bf16_f32 v88, v172, v173
	s_nop 0
	s_waitcnt lgkmcnt(0)
	v_cvt_pk_bf16_f32 v89, v174, v175
	s_nop 0
	s_waitcnt lgkmcnt(0)
	v_cvt_pk_bf16_f32 v90, v176, v177
	s_nop 0
	s_waitcnt lgkmcnt(0)
	v_cvt_pk_bf16_f32 v91, v178, v179
	v_add_u32_e32 v92, 24, v76
	v_ashrrev_i32_e32 v93, 31, v92
	v_lshlrev_b64 v[92:93], 12, v[92:93]
	v_lshl_add_u64 v[92:93], v[74:75], 0, v[92:93]
	global_store_dwordx4 v[92:93], v[88:91], off
	s_nop 0
	s_waitcnt lgkmcnt(0)
	v_cvt_pk_bf16_f32 v88, v180, v181
	s_nop 0
	s_waitcnt lgkmcnt(0)
	v_cvt_pk_bf16_f32 v89, v182, v183
	s_nop 0
	s_waitcnt lgkmcnt(0)
	v_cvt_pk_bf16_f32 v90, v184, v185
	s_nop 0
	s_waitcnt lgkmcnt(0)
	v_cvt_pk_bf16_f32 v91, v186, v187
	v_add_u32_e32 v92, 32, v76
	v_ashrrev_i32_e32 v93, 31, v92
	v_lshlrev_b64 v[92:93], 12, v[92:93]
	v_lshl_add_u64 v[92:93], v[74:75], 0, v[92:93]
	global_store_dwordx4 v[92:93], v[88:91], off
	s_nop 0
	s_waitcnt lgkmcnt(0)
	v_cvt_pk_bf16_f32 v88, v188, v189
	s_nop 0
	s_waitcnt lgkmcnt(0)
	v_cvt_pk_bf16_f32 v89, v190, v191
	s_nop 0
	s_waitcnt lgkmcnt(0)
	v_cvt_pk_bf16_f32 v90, v192, v193
	s_nop 0
	s_waitcnt lgkmcnt(0)
	v_cvt_pk_bf16_f32 v91, v194, v195
	v_add_u32_e32 v92, 40, v76
	v_ashrrev_i32_e32 v93, 31, v92
	v_lshlrev_b64 v[92:93], 12, v[92:93]
	v_lshl_add_u64 v[92:93], v[74:75], 0, v[92:93]
	global_store_dwordx4 v[92:93], v[88:91], off
	s_nop 0
	s_waitcnt lgkmcnt(0)
	v_cvt_pk_bf16_f32 v88, v196, v197
	s_nop 0
	s_waitcnt lgkmcnt(0)
	v_cvt_pk_bf16_f32 v89, v198, v199
	s_nop 0
	s_waitcnt lgkmcnt(0)
	v_cvt_pk_bf16_f32 v90, v210, v211
	s_nop 0
	s_waitcnt lgkmcnt(0)
	v_cvt_pk_bf16_f32 v91, v212, v213
	v_add_u32_e32 v92, 48, v76
	v_ashrrev_i32_e32 v93, 31, v92
	v_lshlrev_b64 v[92:93], 12, v[92:93]
	v_lshl_add_u64 v[92:93], v[74:75], 0, v[92:93]
	v_add_u32_e32 v76, 56, v76
	global_store_dwordx4 v[92:93], v[88:91], off
	s_nop 0
	v_ashrrev_i32_e32 v77, 31, v76
	s_waitcnt lgkmcnt(0)
	v_cvt_pk_bf16_f32 v88, v214, v215
	s_nop 0
	v_lshlrev_b64 v[76:77], 12, v[76:77]
	s_waitcnt lgkmcnt(0)
	v_cvt_pk_bf16_f32 v89, v216, v217
	s_nop 0
	v_lshl_add_u64 v[74:75], v[74:75], 0, v[76:77]
	s_waitcnt lgkmcnt(0)
	v_cvt_pk_bf16_f32 v90, v218, v219
	s_nop 0
	s_waitcnt lgkmcnt(0)
	v_cvt_pk_bf16_f32 v91, v220, v221
	global_store_dwordx4 v[74:75], v[88:91], off
	s_waitcnt lgkmcnt(0)

.LBB0_423:
	v_add_u32_e32 v222, 0x400, v80
	ds_read2_b32 v[148:149], v80 offset1:65
	ds_read2_b32 v[150:151], v80 offset0:130 offset1:195
	ds_read2_b32 v[152:153], v222 offset0:4 offset1:69
	ds_read2_b32 v[154:155], v222 offset0:134 offset1:199
	ds_read2_b32 v[156:157], v80 offset0:8 offset1:73
	ds_read2_b32 v[158:159], v80 offset0:138 offset1:203
	ds_read2_b32 v[160:161], v222 offset0:12 offset1:77
	ds_read2_b32 v[162:163], v222 offset0:142 offset1:207
	ds_read2_b32 v[164:165], v80 offset0:16 offset1:81
	ds_read2_b32 v[166:167], v80 offset0:146 offset1:211
	ds_read2_b32 v[168:169], v222 offset0:20 offset1:85
	ds_read2_b32 v[170:171], v222 offset0:150 offset1:215
	ds_read2_b32 v[172:173], v80 offset0:24 offset1:89
	ds_read2_b32 v[174:175], v80 offset0:154 offset1:219
	ds_read2_b32 v[176:177], v222 offset0:28 offset1:93
	ds_read2_b32 v[178:179], v222 offset0:158 offset1:223
	ds_read2_b32 v[180:181], v80 offset0:32 offset1:97
	ds_read2_b32 v[182:183], v80 offset0:162 offset1:227
	ds_read2_b32 v[184:185], v222 offset0:36 offset1:101
	ds_read2_b32 v[186:187], v222 offset0:166 offset1:231
	ds_read2_b32 v[188:189], v80 offset0:40 offset1:105
	ds_read2_b32 v[190:191], v80 offset0:170 offset1:235
	ds_read2_b32 v[192:193], v222 offset0:44 offset1:109
	ds_read2_b32 v[194:195], v222 offset0:174 offset1:239
	ds_read2_b32 v[196:197], v80 offset0:48 offset1:113
	ds_read2_b32 v[198:199], v80 offset0:178 offset1:243
	ds_read2_b32 v[210:211], v222 offset0:52 offset1:117
	ds_read2_b32 v[212:213], v222 offset0:182 offset1:247
	ds_read2_b32 v[214:215], v80 offset0:56 offset1:121
	ds_read2_b32 v[216:217], v80 offset0:186 offset1:251
	ds_read2_b32 v[218:219], v222 offset0:60 offset1:125
	ds_read2_b32 v[220:221], v222 offset0:190 offset1:255
	s_nop 0
	s_add_i32 s25, s25, s22
	v_add_u32_e32 v58, s25, v79
	v_ashrrev_i32_e32 v59, 31, v58
	v_lshlrev_b64 v[60:61], 12, v[58:59]
	s_waitcnt vmcnt(1) lgkmcnt(0)
	v_mul_f32_e32 v29, v4, v148
	v_mul_f32_e32 v50, v5, v149
	v_cvt_pk_bf16_f32 v52, v29, v50
	s_nop 0
	v_add_u32_e32 v29, 0x400, v80
	s_waitcnt lgkmcnt(0)
	v_mul_f32_e32 v50, v6, v150
	v_mul_f32_e32 v51, v7, v151
	v_cvt_pk_bf16_f32 v53, v50, v51
	s_nop 0
	s_waitcnt vmcnt(0) lgkmcnt(0)
	v_mul_f32_e32 v50, v0, v152
	v_mul_f32_e32 v51, v1, v153
	v_cvt_pk_bf16_f32 v54, v50, v51
	s_nop 0
	v_lshl_add_u64 v[50:51], s[0:1], 1, v[42:43]
	v_lshl_add_u64 v[60:61], v[50:51], 0, v[60:61]
	s_waitcnt lgkmcnt(0)
	v_mul_f32_e32 v55, v2, v154
	v_mul_f32_e32 v56, v3, v155
	v_cvt_pk_bf16_f32 v55, v55, v56
	s_nop 0
	global_store_dwordx4 v[60:61], v[52:55], off
	v_add_u32_e32 v60, 8, v58
	v_ashrrev_i32_e32 v61, 31, v60
	v_lshlrev_b64 v[60:61], 12, v[60:61]
	s_waitcnt lgkmcnt(0)
	v_mul_f32_e32 v52, v4, v156
	v_mul_f32_e32 v53, v5, v157
	v_cvt_pk_bf16_f32 v52, v52, v53
	s_nop 0
	v_lshl_add_u64 v[60:61], v[50:51], 0, v[60:61]
	s_waitcnt lgkmcnt(0)
	v_mul_f32_e32 v53, v6, v158
	v_mul_f32_e32 v54, v7, v159
	v_cvt_pk_bf16_f32 v53, v53, v54
	s_nop 0
	s_waitcnt lgkmcnt(0)
	v_mul_f32_e32 v54, v0, v160
	v_mul_f32_e32 v55, v1, v161
	v_cvt_pk_bf16_f32 v54, v54, v55
	s_nop 0
	s_waitcnt lgkmcnt(0)
	v_mul_f32_e32 v55, v2, v162
	v_mul_f32_e32 v56, v3, v163
	v_cvt_pk_bf16_f32 v55, v55, v56
	s_nop 0
	global_store_dwordx4 v[60:61], v[52:55], off
	v_add_u32_e32 v60, 16, v58
	v_ashrrev_i32_e32 v61, 31, v60
	v_lshlrev_b64 v[60:61], 12, v[60:61]
	s_waitcnt lgkmcnt(0)
	v_mul_f32_e32 v52, v4, v164
	v_mul_f32_e32 v53, v5, v165
	v_cvt_pk_bf16_f32 v52, v52, v53
	s_nop 0
	v_lshl_add_u64 v[60:61], v[50:51], 0, v[60:61]
	s_waitcnt lgkmcnt(0)
	v_mul_f32_e32 v53, v6, v166
	v_mul_f32_e32 v54, v7, v167
	v_cvt_pk_bf16_f32 v53, v53, v54
	s_nop 0
	s_waitcnt lgkmcnt(0)
	v_mul_f32_e32 v54, v0, v168
	v_mul_f32_e32 v55, v1, v169
	v_cvt_pk_bf16_f32 v54, v54, v55
	s_nop 0
	s_waitcnt lgkmcnt(0)
	v_mul_f32_e32 v55, v2, v170
	v_mul_f32_e32 v56, v3, v171
	v_cvt_pk_bf16_f32 v55, v55, v56
	s_nop 0
	global_store_dwordx4 v[60:61], v[52:55], off
	v_add_u32_e32 v60, 24, v58
	v_ashrrev_i32_e32 v61, 31, v60
	v_lshlrev_b64 v[60:61], 12, v[60:61]
	s_waitcnt lgkmcnt(0)
	v_mul_f32_e32 v52, v4, v172
	v_mul_f32_e32 v53, v5, v173
	v_cvt_pk_bf16_f32 v52, v52, v53
	s_nop 0
	v_lshl_add_u64 v[60:61], v[50:51], 0, v[60:61]
	s_waitcnt lgkmcnt(0)
	v_mul_f32_e32 v53, v6, v174
	v_mul_f32_e32 v54, v7, v175
	v_cvt_pk_bf16_f32 v53, v53, v54
	s_nop 0
	s_waitcnt lgkmcnt(0)
	v_mul_f32_e32 v54, v0, v176
	v_mul_f32_e32 v55, v1, v177
	v_cvt_pk_bf16_f32 v54, v54, v55
	s_nop 0
	s_waitcnt lgkmcnt(0)
	v_mul_f32_e32 v55, v2, v178
	v_mul_f32_e32 v56, v3, v179
	v_cvt_pk_bf16_f32 v55, v55, v56
	s_nop 0
	global_store_dwordx4 v[60:61], v[52:55], off
	v_add_u32_e32 v60, 32, v58
	v_ashrrev_i32_e32 v61, 31, v60
	v_lshlrev_b64 v[60:61], 12, v[60:61]
	s_waitcnt lgkmcnt(0)
	v_mul_f32_e32 v52, v4, v180
	v_mul_f32_e32 v53, v5, v181
	v_cvt_pk_bf16_f32 v52, v52, v53
	s_nop 0
	v_lshl_add_u64 v[60:61], v[50:51], 0, v[60:61]
	s_waitcnt lgkmcnt(0)
	v_mul_f32_e32 v53, v6, v182
	v_mul_f32_e32 v54, v7, v183
	v_cvt_pk_bf16_f32 v53, v53, v54
	s_nop 0
	s_waitcnt lgkmcnt(0)
	v_mul_f32_e32 v54, v0, v184
	v_mul_f32_e32 v55, v1, v185
	v_cvt_pk_bf16_f32 v54, v54, v55
	s_nop 0
	s_waitcnt lgkmcnt(0)
	v_mul_f32_e32 v55, v2, v186
	v_mul_f32_e32 v56, v3, v187
	v_cvt_pk_bf16_f32 v55, v55, v56
	s_nop 0
	global_store_dwordx4 v[60:61], v[52:55], off
	v_add_u32_e32 v60, 40, v58
	v_ashrrev_i32_e32 v61, 31, v60
	v_lshlrev_b64 v[60:61], 12, v[60:61]
	s_waitcnt lgkmcnt(0)
	v_mul_f32_e32 v52, v4, v188
	v_mul_f32_e32 v53, v5, v189
	v_cvt_pk_bf16_f32 v52, v52, v53
	s_nop 0
	v_lshl_add_u64 v[60:61], v[50:51], 0, v[60:61]
	s_waitcnt lgkmcnt(0)
	v_mul_f32_e32 v53, v6, v190
	v_mul_f32_e32 v54, v7, v191
	v_cvt_pk_bf16_f32 v53, v53, v54
	s_nop 0
	s_waitcnt lgkmcnt(0)
	v_mul_f32_e32 v54, v0, v192
	v_mul_f32_e32 v55, v1, v193
	v_cvt_pk_bf16_f32 v54, v54, v55
	s_nop 0
	s_waitcnt lgkmcnt(0)
	v_mul_f32_e32 v55, v2, v194
	v_mul_f32_e32 v56, v3, v195
	v_cvt_pk_bf16_f32 v55, v55, v56
	s_nop 0
	global_store_dwordx4 v[60:61], v[52:55], off
	v_add_u32_e32 v60, 48, v58
	v_ashrrev_i32_e32 v61, 31, v60
	v_lshlrev_b64 v[60:61], 12, v[60:61]
	s_waitcnt lgkmcnt(0)
	v_mul_f32_e32 v52, v4, v196
	v_mul_f32_e32 v53, v5, v197
	v_cvt_pk_bf16_f32 v52, v52, v53
	s_nop 0
	v_lshl_add_u64 v[60:61], v[50:51], 0, v[60:61]
	s_waitcnt lgkmcnt(0)
	v_mul_f32_e32 v53, v6, v198
	v_mul_f32_e32 v54, v7, v199
	v_cvt_pk_bf16_f32 v53, v53, v54
	s_nop 0
	s_waitcnt lgkmcnt(0)
	v_mul_f32_e32 v54, v0, v210
	v_mul_f32_e32 v55, v1, v211
	v_cvt_pk_bf16_f32 v54, v54, v55
	s_nop 0
	s_waitcnt lgkmcnt(0)
	v_mul_f32_e32 v55, v2, v212
	v_mul_f32_e32 v56, v3, v213
	v_cvt_pk_bf16_f32 v55, v55, v56
	s_nop 0
	global_store_dwordx4 v[60:61], v[52:55], off
	s_waitcnt lgkmcnt(0)
	v_mul_f32_e32 v4, v4, v214
	v_mul_f32_e32 v5, v5, v215
	v_cvt_pk_bf16_f32 v4, v4, v5
	s_nop 0
	s_waitcnt lgkmcnt(0)
	v_mul_f32_e32 v5, v6, v216
	v_mul_f32_e32 v6, v7, v217
	v_cvt_pk_bf16_f32 v5, v5, v6
	s_nop 0
	v_add_u32_e32 v52, 56, v58
	v_ashrrev_i32_e32 v53, 31, v52
	v_lshlrev_b64 v[52:53], 12, v[52:53]
	s_waitcnt lgkmcnt(0)
	v_mul_f32_e32 v0, v0, v218
	v_mul_f32_e32 v1, v1, v219
	v_cvt_pk_bf16_f32 v6, v0, v1
	s_nop 0
	s_waitcnt lgkmcnt(0)
	v_mul_f32_e32 v0, v2, v220
	v_mul_f32_e32 v1, v3, v221
	v_cvt_pk_bf16_f32 v7, v0, v1
	v_lshl_add_u64 v[0:1], v[50:51], 0, v[52:53]
	global_store_dwordx4 v[0:1], v[4:7], off
	s_waitcnt lgkmcnt(0)

.LBB0_429:
	v_add_u32_e32 v222, 0x400, v80
	ds_read2_b32 v[148:149], v80 offset1:65
	ds_read2_b32 v[150:151], v80 offset0:130 offset1:195
	ds_read2_b32 v[152:153], v222 offset0:4 offset1:69
	ds_read2_b32 v[154:155], v222 offset0:134 offset1:199
	ds_read2_b32 v[156:157], v80 offset0:8 offset1:73
	ds_read2_b32 v[158:159], v80 offset0:138 offset1:203
	ds_read2_b32 v[160:161], v222 offset0:12 offset1:77
	ds_read2_b32 v[162:163], v222 offset0:142 offset1:207
	ds_read2_b32 v[164:165], v80 offset0:16 offset1:81
	ds_read2_b32 v[166:167], v80 offset0:146 offset1:211
	ds_read2_b32 v[168:169], v222 offset0:20 offset1:85
	ds_read2_b32 v[170:171], v222 offset0:150 offset1:215
	ds_read2_b32 v[172:173], v80 offset0:24 offset1:89
	ds_read2_b32 v[174:175], v80 offset0:154 offset1:219
	ds_read2_b32 v[176:177], v222 offset0:28 offset1:93
	ds_read2_b32 v[178:179], v222 offset0:158 offset1:223
	ds_read2_b32 v[180:181], v80 offset0:32 offset1:97
	ds_read2_b32 v[182:183], v80 offset0:162 offset1:227
	ds_read2_b32 v[184:185], v222 offset0:36 offset1:101
	ds_read2_b32 v[186:187], v222 offset0:166 offset1:231
	ds_read2_b32 v[188:189], v80 offset0:40 offset1:105
	ds_read2_b32 v[190:191], v80 offset0:170 offset1:235
	ds_read2_b32 v[192:193], v222 offset0:44 offset1:109
	ds_read2_b32 v[194:195], v222 offset0:174 offset1:239
	ds_read2_b32 v[196:197], v80 offset0:48 offset1:113
	ds_read2_b32 v[198:199], v80 offset0:178 offset1:243
	ds_read2_b32 v[210:211], v222 offset0:52 offset1:117
	ds_read2_b32 v[212:213], v222 offset0:182 offset1:247
	ds_read2_b32 v[214:215], v80 offset0:56 offset1:121
	ds_read2_b32 v[216:217], v80 offset0:186 offset1:251
	ds_read2_b32 v[218:219], v222 offset0:60 offset1:125
	ds_read2_b32 v[220:221], v222 offset0:190 offset1:255
	s_nop 0
	s_sub_i32 s4, 0, s25
	s_add_i32 s4, s4, s22
	v_add_u32_e32 v58, s4, v79
	v_ashrrev_i32_e32 v59, 31, v58
	s_waitcnt vmcnt(1) lgkmcnt(0)
	v_mul_f32_e32 v29, v4, v148
	v_mul_f32_e32 v50, v5, v149
	v_cvt_pk_bf16_f32 v52, v29, v50
	s_nop 0
	v_add_u32_e32 v29, 0x400, v80
	v_lshlrev_b64 v[60:61], 12, v[58:59]
	s_waitcnt lgkmcnt(0)
	v_mul_f32_e32 v50, v6, v150
	v_mul_f32_e32 v51, v7, v151
	v_cvt_pk_bf16_f32 v53, v50, v51
	s_nop 0
	s_waitcnt vmcnt(0) lgkmcnt(0)
	v_mul_f32_e32 v50, v0, v152
	v_mul_f32_e32 v51, v1, v153
	v_cvt_pk_bf16_f32 v54, v50, v51
	s_nop 0
	v_lshl_add_u64 v[50:51], s[0:1], 1, v[20:21]
	v_lshl_add_u64 v[60:61], v[50:51], 0, v[60:61]
	s_waitcnt lgkmcnt(0)
	v_mul_f32_e32 v55, v2, v154
	v_mul_f32_e32 v56, v3, v155
	v_cvt_pk_bf16_f32 v55, v55, v56
	s_nop 0
	global_store_dwordx4 v[60:61], v[52:55], off
	v_add_u32_e32 v60, 8, v58
	v_ashrrev_i32_e32 v61, 31, v60
	v_lshlrev_b64 v[60:61], 12, v[60:61]
	s_waitcnt lgkmcnt(0)
	v_mul_f32_e32 v52, v4, v156
	v_mul_f32_e32 v53, v5, v157
	v_cvt_pk_bf16_f32 v52, v52, v53
	s_nop 0
	v_lshl_add_u64 v[60:61], v[50:51], 0, v[60:61]
	s_waitcnt lgkmcnt(0)
	v_mul_f32_e32 v53, v6, v158
	v_mul_f32_e32 v54, v7, v159
	v_cvt_pk_bf16_f32 v53, v53, v54
	s_nop 0
	s_waitcnt lgkmcnt(0)
	v_mul_f32_e32 v54, v0, v160
	v_mul_f32_e32 v55, v1, v161
	v_cvt_pk_bf16_f32 v54, v54, v55
	s_nop 0
	s_waitcnt lgkmcnt(0)
	v_mul_f32_e32 v55, v2, v162
	v_mul_f32_e32 v56, v3, v163
	v_cvt_pk_bf16_f32 v55, v55, v56
	s_nop 0
	global_store_dwordx4 v[60:61], v[52:55], off
	v_add_u32_e32 v60, 16, v58
	v_ashrrev_i32_e32 v61, 31, v60
	v_lshlrev_b64 v[60:61], 12, v[60:61]
	s_waitcnt lgkmcnt(0)
	v_mul_f32_e32 v52, v4, v164
	v_mul_f32_e32 v53, v5, v165
	v_cvt_pk_bf16_f32 v52, v52, v53
	s_nop 0
	v_lshl_add_u64 v[60:61], v[50:51], 0, v[60:61]
	s_waitcnt lgkmcnt(0)
	v_mul_f32_e32 v53, v6, v166
	v_mul_f32_e32 v54, v7, v167
	v_cvt_pk_bf16_f32 v53, v53, v54
	s_nop 0
	s_waitcnt lgkmcnt(0)
	v_mul_f32_e32 v54, v0, v168
	v_mul_f32_e32 v55, v1, v169
	v_cvt_pk_bf16_f32 v54, v54, v55
	s_nop 0
	s_waitcnt lgkmcnt(0)
	v_mul_f32_e32 v55, v2, v170
	v_mul_f32_e32 v56, v3, v171
	v_cvt_pk_bf16_f32 v55, v55, v56
	s_nop 0
	global_store_dwordx4 v[60:61], v[52:55], off
	v_add_u32_e32 v60, 24, v58
	v_ashrrev_i32_e32 v61, 31, v60
	v_lshlrev_b64 v[60:61], 12, v[60:61]
	s_waitcnt lgkmcnt(0)
	v_mul_f32_e32 v52, v4, v172
	v_mul_f32_e32 v53, v5, v173
	v_cvt_pk_bf16_f32 v52, v52, v53
	s_nop 0
	v_lshl_add_u64 v[60:61], v[50:51], 0, v[60:61]
	s_waitcnt lgkmcnt(0)
	v_mul_f32_e32 v53, v6, v174
	v_mul_f32_e32 v54, v7, v175
	v_cvt_pk_bf16_f32 v53, v53, v54
	s_nop 0
	s_waitcnt lgkmcnt(0)
	v_mul_f32_e32 v54, v0, v176
	v_mul_f32_e32 v55, v1, v177
	v_cvt_pk_bf16_f32 v54, v54, v55
	s_nop 0
	s_waitcnt lgkmcnt(0)
	v_mul_f32_e32 v55, v2, v178
	v_mul_f32_e32 v56, v3, v179
	v_cvt_pk_bf16_f32 v55, v55, v56
	s_nop 0
	global_store_dwordx4 v[60:61], v[52:55], off
	v_add_u32_e32 v60, 32, v58
	v_ashrrev_i32_e32 v61, 31, v60
	v_lshlrev_b64 v[60:61], 12, v[60:61]
	s_waitcnt lgkmcnt(0)
	v_mul_f32_e32 v52, v4, v180
	v_mul_f32_e32 v53, v5, v181
	v_cvt_pk_bf16_f32 v52, v52, v53
	s_nop 0
	v_lshl_add_u64 v[60:61], v[50:51], 0, v[60:61]
	s_waitcnt lgkmcnt(0)
	v_mul_f32_e32 v53, v6, v182
	v_mul_f32_e32 v54, v7, v183
	v_cvt_pk_bf16_f32 v53, v53, v54
	s_nop 0
	s_waitcnt lgkmcnt(0)
	v_mul_f32_e32 v54, v0, v184
	v_mul_f32_e32 v55, v1, v185
	v_cvt_pk_bf16_f32 v54, v54, v55
	s_nop 0
	s_waitcnt lgkmcnt(0)
	v_mul_f32_e32 v55, v2, v186
	v_mul_f32_e32 v56, v3, v187
	v_cvt_pk_bf16_f32 v55, v55, v56
	s_nop 0
	global_store_dwordx4 v[60:61], v[52:55], off
	v_add_u32_e32 v60, 40, v58
	v_ashrrev_i32_e32 v61, 31, v60
	v_lshlrev_b64 v[60:61], 12, v[60:61]
	s_waitcnt lgkmcnt(0)
	v_mul_f32_e32 v52, v4, v188
	v_mul_f32_e32 v53, v5, v189
	v_cvt_pk_bf16_f32 v52, v52, v53
	s_nop 0
	v_lshl_add_u64 v[60:61], v[50:51], 0, v[60:61]
	s_waitcnt lgkmcnt(0)
	v_mul_f32_e32 v53, v6, v190
	v_mul_f32_e32 v54, v7, v191
	v_cvt_pk_bf16_f32 v53, v53, v54
	s_nop 0
	s_waitcnt lgkmcnt(0)
	v_mul_f32_e32 v54, v0, v192
	v_mul_f32_e32 v55, v1, v193
	v_cvt_pk_bf16_f32 v54, v54, v55
	s_nop 0
	s_waitcnt lgkmcnt(0)
	v_mul_f32_e32 v55, v2, v194
	v_mul_f32_e32 v56, v3, v195
	v_cvt_pk_bf16_f32 v55, v55, v56
	s_nop 0
	global_store_dwordx4 v[60:61], v[52:55], off
	v_add_u32_e32 v60, 48, v58
	v_ashrrev_i32_e32 v61, 31, v60
	v_lshlrev_b64 v[60:61], 12, v[60:61]
	s_waitcnt lgkmcnt(0)
	v_mul_f32_e32 v52, v4, v196
	v_mul_f32_e32 v53, v5, v197
	v_cvt_pk_bf16_f32 v52, v52, v53
	s_nop 0
	v_lshl_add_u64 v[60:61], v[50:51], 0, v[60:61]
	s_waitcnt lgkmcnt(0)
	v_mul_f32_e32 v53, v6, v198
	v_mul_f32_e32 v54, v7, v199
	v_cvt_pk_bf16_f32 v53, v53, v54
	s_nop 0
	s_waitcnt lgkmcnt(0)
	v_mul_f32_e32 v54, v0, v210
	v_mul_f32_e32 v55, v1, v211
	v_cvt_pk_bf16_f32 v54, v54, v55
	s_nop 0
	s_waitcnt lgkmcnt(0)
	v_mul_f32_e32 v55, v2, v212
	v_mul_f32_e32 v56, v3, v213
	v_cvt_pk_bf16_f32 v55, v55, v56
	s_nop 0
	global_store_dwordx4 v[60:61], v[52:55], off
	s_waitcnt lgkmcnt(0)
	v_mul_f32_e32 v4, v4, v214
	v_mul_f32_e32 v5, v5, v215
	v_cvt_pk_bf16_f32 v4, v4, v5
	s_nop 0
	s_waitcnt lgkmcnt(0)
	v_mul_f32_e32 v5, v6, v216
	v_mul_f32_e32 v6, v7, v217
	v_cvt_pk_bf16_f32 v5, v5, v6
	s_nop 0
	v_add_u32_e32 v52, 56, v58
	v_ashrrev_i32_e32 v53, 31, v52
	v_lshlrev_b64 v[52:53], 12, v[52:53]
	s_waitcnt lgkmcnt(0)
	v_mul_f32_e32 v0, v0, v218
	v_mul_f32_e32 v1, v1, v219
	v_cvt_pk_bf16_f32 v6, v0, v1
	s_nop 0
	s_waitcnt lgkmcnt(0)
	v_mul_f32_e32 v0, v2, v220
	v_mul_f32_e32 v1, v3, v221
	v_cvt_pk_bf16_f32 v7, v0, v1
	v_lshl_add_u64 v[0:1], v[50:51], 0, v[52:53]
	global_store_dwordx4 v[0:1], v[4:7], off
	s_waitcnt lgkmcnt(0)

.LBB0_431:
	s_andn2_b64 vcc, exec, s[0:1]
	s_cbranch_vccnz .LBB0_433
	s_load_dwordx2 s[0:1], s[30:31], 0x98
	v_lshlrev_b32_e32 v204, 2, v8
	v_add_u32_e32 v29, 0x410, v78
	s_waitcnt lgkmcnt(0)
	s_add_u32 s5, s0, s53
	s_addc_u32 s25, s1, s52
	s_ashr_i32 s0, s49, 31
	s_lshr_b32 s0, s0, 27
	s_add_i32 s0, s49, s0
	s_ashr_i32 s0, s0, 5
	s_lshl_b32 s1, s0, 11
	s_lshl_b32 s4, s0, 6
	s_sub_i32 s0, s22, s1
	s_ashr_i32 s1, s0, 31
	v_or_b32_e32 v112, s4, v11
	s_lshl_b64 s[6:7], s[0:1], 2
	s_add_u32 s6, s5, s6
	v_or_b32_e32 v2, 4, v112
	s_addc_u32 s7, s25, s7
	v_ashrrev_i32_e32 v113, 31, v112
	v_ashrrev_i32_e32 v3, 31, v2
	v_lshl_add_u64 v[114:115], s[6:7], 0, v[204:205]
	v_lshlrev_b64 v[0:1], 13, v[112:113]
	v_lshlrev_b64 v[2:3], 13, v[2:3]
	v_lshl_add_u64 v[0:1], v[114:115], 0, v[0:1]
	v_lshl_add_u64 v[4:5], v[114:115], 0, v[2:3]
	v_or_b32_e32 v50, 8, v112
	v_or_b32_e32 v52, 12, v112
	global_load_dwordx4 v[0:3], v[0:1], off
	s_nop 0
	global_load_dwordx4 v[4:7], v[4:5], off
	v_ashrrev_i32_e32 v51, 31, v50
	v_ashrrev_i32_e32 v53, 31, v52
	v_lshlrev_b64 v[50:51], 13, v[50:51]
	v_lshlrev_b64 v[52:53], 13, v[52:53]
	v_lshl_add_u64 v[50:51], v[114:115], 0, v[50:51]
	v_lshl_add_u64 v[54:55], v[114:115], 0, v[52:53]
	global_load_dwordx4 v[50:53], v[50:51], off
	s_nop 0
	global_load_dwordx4 v[54:57], v[54:55], off
	v_or_b32_e32 v58, 16, v112
	v_or_b32_e32 v60, 20, v112
	v_ashrrev_i32_e32 v59, 31, v58
	v_ashrrev_i32_e32 v61, 31, v60
	v_lshlrev_b64 v[58:59], 13, v[58:59]
	v_lshlrev_b64 v[60:61], 13, v[60:61]
	v_lshl_add_u64 v[58:59], v[114:115], 0, v[58:59]
	v_lshl_add_u64 v[62:63], v[114:115], 0, v[60:61]
	global_load_dwordx4 v[58:61], v[58:59], off
	s_nop 0
	global_load_dwordx4 v[62:65], v[62:63], off
	v_or_b32_e32 v66, 24, v112
	v_or_b32_e32 v68, 28, v112
	v_ashrrev_i32_e32 v67, 31, v66
	v_ashrrev_i32_e32 v69, 31, v68
	v_lshlrev_b64 v[66:67], 13, v[66:67]
	v_lshlrev_b64 v[68:69], 13, v[68:69]
	v_lshl_add_u64 v[66:67], v[114:115], 0, v[66:67]
	v_lshl_add_u64 v[70:71], v[114:115], 0, v[68:69]
	global_load_dwordx4 v[66:69], v[66:67], off
	s_nop 0
	global_load_dwordx4 v[70:73], v[70:71], off
	v_or_b32_e32 v74, 32, v112
	v_or_b32_e32 v76, 36, v112
	v_ashrrev_i32_e32 v75, 31, v74
	v_ashrrev_i32_e32 v77, 31, v76
	v_lshlrev_b64 v[74:75], 13, v[74:75]
	v_lshlrev_b64 v[76:77], 13, v[76:77]
	v_lshl_add_u64 v[74:75], v[114:115], 0, v[74:75]
	v_lshl_add_u64 v[88:89], v[114:115], 0, v[76:77]
	global_load_dwordx4 v[74:77], v[74:75], off
	s_nop 0
	global_load_dwordx4 v[88:91], v[88:89], off
	v_or_b32_e32 v92, 40, v112
	v_or_b32_e32 v94, 44, v112
	v_ashrrev_i32_e32 v93, 31, v92
	v_ashrrev_i32_e32 v95, 31, v94
	v_lshlrev_b64 v[92:93], 13, v[92:93]
	v_lshlrev_b64 v[94:95], 13, v[94:95]
	v_lshl_add_u64 v[92:93], v[114:115], 0, v[92:93]
	v_lshl_add_u64 v[96:97], v[114:115], 0, v[94:95]
	v_or_b32_e32 v100, 48, v112
	global_load_dwordx4 v[92:95], v[92:93], off
	s_nop 0
	global_load_dwordx4 v[96:99], v[96:97], off
	v_ashrrev_i32_e32 v101, 31, v100
	v_lshlrev_b64 v[100:101], 13, v[100:101]
	v_or_b32_e32 v104, 52, v112
	v_lshl_add_u64 v[100:101], v[114:115], 0, v[100:101]
	v_ashrrev_i32_e32 v105, 31, v104
	global_load_dwordx4 v[100:103], v[100:101], off
	v_lshlrev_b64 v[104:105], 13, v[104:105]
	v_or_b32_e32 v108, 56, v112
	v_lshl_add_u64 v[104:105], v[114:115], 0, v[104:105]
	v_ashrrev_i32_e32 v109, 31, v108
	global_load_dwordx4 v[104:107], v[104:105], off
	v_lshlrev_b64 v[108:109], 13, v[108:109]
	v_or_b32_e32 v112, 60, v112
	v_lshl_add_u64 v[108:109], v[114:115], 0, v[108:109]
	v_ashrrev_i32_e32 v113, 31, v112
	global_load_dwordx4 v[108:111], v[108:109], off
	v_lshlrev_b64 v[112:113], 13, v[112:113]
	v_lshl_add_u64 v[112:113], v[114:115], 0, v[112:113]
	global_load_dwordx4 v[112:115], v[112:113], off
	s_ashr_i32 s5, s4, 31
	s_waitcnt vmcnt(0)
	ds_write2_b32 v78, v0, v1 offset1:1
	ds_write2_b32 v78, v2, v3 offset0:2 offset1:3
	ds_write2_b32 v29, v4, v5 offset1:1
	v_add_u32_e32 v0, 0x418, v78
	ds_write2_b32 v0, v6, v7 offset1:1
	v_add_u32_e32 v0, 0x820, v78
	v_add_u32_e32 v29, 0x400, v80
	v_lshl_add_u64 v[6:7], s[4:5], 1, v[32:33]
	ds_write2_b32 v0, v50, v51 offset1:1
	v_add_u32_e32 v0, 0x828, v78
	ds_write2_b32 v0, v52, v53 offset1:1
	v_add_u32_e32 v0, 0xc30, v78
	ds_write2_b32 v0, v54, v55 offset1:1
	v_add_u32_e32 v0, 0xc38, v78
	ds_write2_b32 v0, v56, v57 offset1:1
	v_add_u32_e32 v0, 0x1040, v78
	v_add_u32_e32 v52, s0, v79
	ds_write2_b32 v0, v58, v59 offset1:1
	v_add_u32_e32 v0, 0x1048, v78
	ds_write2_b32 v0, v60, v61 offset1:1
	v_add_u32_e32 v0, 0x1450, v78
	ds_write2_b32 v0, v62, v63 offset1:1
	v_add_u32_e32 v0, 0x1458, v78
	ds_write2_b32 v0, v64, v65 offset1:1
	v_add_u32_e32 v0, 0x1860, v78
	v_mad_i64_i32 v[50:51], s[0:1], v52, s68, v[6:7]
	ds_write2_b32 v0, v66, v67 offset1:1
	v_add_u32_e32 v0, 0x1868, v78
	ds_write2_b32 v0, v68, v69 offset1:1
	v_add_u32_e32 v0, 0x1c70, v78
	ds_write2_b32 v0, v70, v71 offset1:1
	v_add_u32_e32 v0, 0x1c78, v78
	ds_write2_b32 v0, v72, v73 offset1:1
	v_add_u32_e32 v0, 0x2080, v78
	ds_write2_b32 v0, v74, v75 offset1:1
	v_add_u32_e32 v0, 0x2088, v78
	ds_write2_b32 v0, v76, v77 offset1:1
	v_add_u32_e32 v0, 0x2490, v78
	ds_write2_b32 v0, v88, v89 offset1:1
	v_add_u32_e32 v0, 0x2498, v78
	ds_write2_b32 v0, v90, v91 offset1:1
	v_add_u32_e32 v0, 0x28a0, v78
	ds_write2_b32 v0, v92, v93 offset1:1
	v_add_u32_e32 v0, 0x28a8, v78
	ds_write2_b32 v0, v94, v95 offset1:1
	v_add_u32_e32 v0, 0x2cb0, v78
	ds_write2_b32 v0, v96, v97 offset1:1
	v_add_u32_e32 v0, 0x2cb8, v78
	ds_write2_b32 v0, v98, v99 offset1:1
	v_add_u32_e32 v0, 0x30c0, v78
	ds_write2_b32 v0, v100, v101 offset1:1
	v_add_u32_e32 v0, 0x30c8, v78
	ds_write2_b32 v0, v102, v103 offset1:1
	v_add_u32_e32 v0, 0x34d0, v78
	ds_write2_b32 v0, v104, v105 offset1:1
	v_add_u32_e32 v0, 0x34d8, v78
	ds_write2_b32 v0, v106, v107 offset1:1
	v_add_u32_e32 v0, 0x38e0, v78
	ds_write2_b32 v0, v108, v109 offset1:1
	v_add_u32_e32 v0, 0x38e8, v78
	ds_write2_b32 v0, v110, v111 offset1:1
	v_add_u32_e32 v0, 0x3cf0, v78
	ds_write2_b32 v0, v112, v113 offset1:1
	v_add_u32_e32 v0, 0x3cf8, v78
	ds_write2_b32 v0, v114, v115 offset1:1
	s_waitcnt lgkmcnt(0)
	ds_read2_b32 v[148:149], v80 offset1:65
	ds_read2_b32 v[150:151], v80 offset0:130 offset1:195
	ds_read2_b32 v[152:153], v29 offset0:4 offset1:69
	ds_read2_b32 v[154:155], v29 offset0:134 offset1:199
	ds_read2_b32 v[156:157], v80 offset0:8 offset1:73
	ds_read2_b32 v[158:159], v80 offset0:138 offset1:203
	ds_read2_b32 v[160:161], v29 offset0:12 offset1:77
	ds_read2_b32 v[162:163], v29 offset0:142 offset1:207
	ds_read2_b32 v[164:165], v80 offset0:16 offset1:81
	ds_read2_b32 v[166:167], v80 offset0:146 offset1:211
	ds_read2_b32 v[168:169], v29 offset0:20 offset1:85
	ds_read2_b32 v[170:171], v29 offset0:150 offset1:215
	ds_read2_b32 v[172:173], v80 offset0:24 offset1:89
	ds_read2_b32 v[174:175], v80 offset0:154 offset1:219
	ds_read2_b32 v[176:177], v29 offset0:28 offset1:93
	ds_read2_b32 v[178:179], v29 offset0:158 offset1:223
	ds_read2_b32 v[180:181], v80 offset0:32 offset1:97
	ds_read2_b32 v[182:183], v80 offset0:162 offset1:227
	ds_read2_b32 v[184:185], v29 offset0:36 offset1:101
	ds_read2_b32 v[186:187], v29 offset0:166 offset1:231
	ds_read2_b32 v[188:189], v80 offset0:40 offset1:105
	ds_read2_b32 v[190:191], v80 offset0:170 offset1:235
	ds_read2_b32 v[192:193], v29 offset0:44 offset1:109
	ds_read2_b32 v[194:195], v29 offset0:174 offset1:239
	ds_read2_b32 v[196:197], v80 offset0:48 offset1:113
	ds_read2_b32 v[198:199], v80 offset0:178 offset1:243
	ds_read2_b32 v[210:211], v29 offset0:52 offset1:117
	ds_read2_b32 v[212:213], v29 offset0:182 offset1:247
	ds_read2_b32 v[214:215], v80 offset0:56 offset1:121
	ds_read2_b32 v[216:217], v80 offset0:186 offset1:251
	ds_read2_b32 v[218:219], v29 offset0:60 offset1:125
	ds_read2_b32 v[220:221], v29 offset0:190 offset1:255
	s_nop 0
	s_waitcnt lgkmcnt(0)
	v_cvt_pk_bf16_f32 v0, v148, v149
	s_nop 0
	s_waitcnt lgkmcnt(0)
	v_cvt_pk_bf16_f32 v1, v150, v151
	s_nop 0
	s_waitcnt lgkmcnt(0)
	v_cvt_pk_bf16_f32 v2, v152, v153
	s_nop 0
	s_waitcnt lgkmcnt(0)
	v_cvt_pk_bf16_f32 v3, v154, v155
	s_nop 0
	global_store_dwordx4 v[50:51], v[0:3], off
	v_add_u32_e32 v50, 8, v52
	v_mad_i64_i32 v[50:51], s[0:1], v50, s68, v[6:7]
	s_waitcnt lgkmcnt(0)
	v_cvt_pk_bf16_f32 v0, v156, v157
	s_nop 0
	s_waitcnt lgkmcnt(0)
	v_cvt_pk_bf16_f32 v1, v158, v159
	s_nop 0
	s_waitcnt lgkmcnt(0)
	v_cvt_pk_bf16_f32 v2, v160, v161
	s_nop 0
	s_waitcnt lgkmcnt(0)
	v_cvt_pk_bf16_f32 v3, v162, v163
	s_nop 0
	global_store_dwordx4 v[50:51], v[0:3], off
	v_add_u32_e32 v50, 16, v52
	v_mad_i64_i32 v[50:51], s[0:1], v50, s68, v[6:7]
	s_waitcnt lgkmcnt(0)
	v_cvt_pk_bf16_f32 v0, v164, v165
	s_nop 0
	s_waitcnt lgkmcnt(0)
	v_cvt_pk_bf16_f32 v1, v166, v167
	s_nop 0
	s_waitcnt lgkmcnt(0)
	v_cvt_pk_bf16_f32 v2, v168, v169
	s_nop 0
	s_waitcnt lgkmcnt(0)
	v_cvt_pk_bf16_f32 v3, v170, v171
	s_nop 0
	global_store_dwordx4 v[50:51], v[0:3], off
	v_add_u32_e32 v50, 24, v52
	v_mad_i64_i32 v[50:51], s[0:1], v50, s68, v[6:7]
	s_waitcnt lgkmcnt(0)
	v_cvt_pk_bf16_f32 v0, v172, v173
	s_nop 0
	s_waitcnt lgkmcnt(0)
	v_cvt_pk_bf16_f32 v1, v174, v175
	s_nop 0
	s_waitcnt lgkmcnt(0)
	v_cvt_pk_bf16_f32 v2, v176, v177
	s_nop 0
	s_waitcnt lgkmcnt(0)
	v_cvt_pk_bf16_f32 v3, v178, v179
	s_nop 0
	global_store_dwordx4 v[50:51], v[0:3], off
	v_add_u32_e32 v50, 32, v52
	v_mad_i64_i32 v[50:51], s[0:1], v50, s68, v[6:7]
	s_waitcnt lgkmcnt(0)
	v_cvt_pk_bf16_f32 v0, v180, v181
	s_nop 0
	s_waitcnt lgkmcnt(0)
	v_cvt_pk_bf16_f32 v1, v182, v183
	s_nop 0
	s_waitcnt lgkmcnt(0)
	v_cvt_pk_bf16_f32 v2, v184, v185
	s_nop 0
	s_waitcnt lgkmcnt(0)
	v_cvt_pk_bf16_f32 v3, v186, v187
	s_nop 0
	global_store_dwordx4 v[50:51], v[0:3], off
	v_add_u32_e32 v50, 40, v52
	v_mad_i64_i32 v[50:51], s[0:1], v50, s68, v[6:7]
	s_waitcnt lgkmcnt(0)
	v_cvt_pk_bf16_f32 v0, v188, v189
	s_nop 0
	s_waitcnt lgkmcnt(0)
	v_cvt_pk_bf16_f32 v1, v190, v191
	s_nop 0
	s_waitcnt lgkmcnt(0)
	v_cvt_pk_bf16_f32 v2, v192, v193
	s_nop 0
	s_waitcnt lgkmcnt(0)
	v_cvt_pk_bf16_f32 v3, v194, v195
	s_nop 0
	global_store_dwordx4 v[50:51], v[0:3], off
	v_add_u32_e32 v50, 48, v52
	v_mad_i64_i32 v[50:51], s[0:1], v50, s68, v[6:7]
	s_waitcnt lgkmcnt(0)
	v_cvt_pk_bf16_f32 v0, v196, v197
	s_nop 0
	s_waitcnt lgkmcnt(0)
	v_cvt_pk_bf16_f32 v1, v198, v199
	s_nop 0
	s_waitcnt lgkmcnt(0)
	v_cvt_pk_bf16_f32 v2, v210, v211
	s_nop 0
	s_waitcnt lgkmcnt(0)
	v_cvt_pk_bf16_f32 v3, v212, v213
	s_nop 0
	global_store_dwordx4 v[50:51], v[0:3], off
	s_waitcnt lgkmcnt(0)
	s_nop 0
	v_cvt_pk_bf16_f32 v0, v214, v215
	s_nop 0
	s_waitcnt lgkmcnt(0)
	v_cvt_pk_bf16_f32 v1, v216, v217
	s_nop 0
	s_waitcnt lgkmcnt(0)
	v_cvt_pk_bf16_f32 v2, v218, v219
	s_nop 0
	v_add_u32_e32 v29, 56, v52
	s_waitcnt lgkmcnt(0)
	v_cvt_pk_bf16_f32 v3, v220, v221
	v_mad_i64_i32 v[4:5], s[0:1], v29, s68, v[6:7]
	global_store_dwordx4 v[4:5], v[0:3], off
	s_waitcnt lgkmcnt(0)

.LBB0_438:
	v_add_u32_e32 v222, 0x400, v80
	ds_read2_b32 v[148:149], v80 offset1:65
	ds_read2_b32 v[150:151], v80 offset0:130 offset1:195
	ds_read2_b32 v[152:153], v222 offset0:4 offset1:69
	ds_read2_b32 v[154:155], v222 offset0:134 offset1:199
	ds_read2_b32 v[156:157], v80 offset0:8 offset1:73
	ds_read2_b32 v[158:159], v80 offset0:138 offset1:203
	ds_read2_b32 v[160:161], v222 offset0:12 offset1:77
	ds_read2_b32 v[162:163], v222 offset0:142 offset1:207
	ds_read2_b32 v[164:165], v80 offset0:16 offset1:81
	ds_read2_b32 v[166:167], v80 offset0:146 offset1:211
	ds_read2_b32 v[168:169], v222 offset0:20 offset1:85
	ds_read2_b32 v[170:171], v222 offset0:150 offset1:215
	ds_read2_b32 v[172:173], v80 offset0:24 offset1:89
	ds_read2_b32 v[174:175], v80 offset0:154 offset1:219
	ds_read2_b32 v[176:177], v222 offset0:28 offset1:93
	ds_read2_b32 v[178:179], v222 offset0:158 offset1:223
	ds_read2_b32 v[180:181], v80 offset0:32 offset1:97
	ds_read2_b32 v[182:183], v80 offset0:162 offset1:227
	ds_read2_b32 v[184:185], v222 offset0:36 offset1:101
	ds_read2_b32 v[186:187], v222 offset0:166 offset1:231
	ds_read2_b32 v[188:189], v80 offset0:40 offset1:105
	ds_read2_b32 v[190:191], v80 offset0:170 offset1:235
	ds_read2_b32 v[192:193], v222 offset0:44 offset1:109
	ds_read2_b32 v[194:195], v222 offset0:174 offset1:239
	ds_read2_b32 v[196:197], v80 offset0:48 offset1:113
	ds_read2_b32 v[198:199], v80 offset0:178 offset1:243
	ds_read2_b32 v[210:211], v222 offset0:52 offset1:117
	ds_read2_b32 v[212:213], v222 offset0:182 offset1:247
	ds_read2_b32 v[214:215], v80 offset0:56 offset1:121
	ds_read2_b32 v[216:217], v80 offset0:186 offset1:251
	ds_read2_b32 v[218:219], v222 offset0:60 offset1:125
	ds_read2_b32 v[220:221], v222 offset0:190 offset1:255
	s_nop 0
	s_and_b32 s5, s22, 64
	s_mulk_i32 s4, 0x2c00
	s_waitcnt vmcnt(1) lgkmcnt(0)
	v_mul_f32_e32 v29, v4, v148
	v_mul_f32_e32 v50, v5, v149
	v_cvt_pk_bf16_f32 v52, v29, v50
	s_nop 0
	v_add_u32_e32 v29, 0x400, v80
	s_waitcnt lgkmcnt(0)
	v_mul_f32_e32 v50, v6, v150
	v_mul_f32_e32 v51, v7, v151
	v_cvt_pk_bf16_f32 v53, v50, v51
	s_nop 0
	v_lshl_add_u64 v[50:51], s[0:1], 1, v[44:45]
	s_sub_i32 s0, s5, s4
	s_add_i32 s0, s60, s0
	s_bitset1_b32 s0, 7
	s_waitcnt vmcnt(0) lgkmcnt(0)
	v_mul_f32_e32 v54, v0, v152
	v_mul_f32_e32 v55, v1, v153
	v_cvt_pk_bf16_f32 v54, v54, v55
	s_nop 0
	v_or_b32_e32 v58, s0, v79
	v_ashrrev_i32_e32 v59, 31, v58
	v_lshlrev_b64 v[58:59], 12, v[58:59]
	v_lshl_add_u64 v[58:59], v[50:51], 0, v[58:59]
	s_waitcnt lgkmcnt(0)
	v_mul_f32_e32 v55, v2, v154
	v_mul_f32_e32 v56, v3, v155
	v_cvt_pk_bf16_f32 v55, v55, v56
	s_nop 0
	global_store_dwordx4 v[58:59], v[52:55], off
	v_or_b32_e32 v58, s0, v81
	v_ashrrev_i32_e32 v59, 31, v58
	v_lshlrev_b64 v[58:59], 12, v[58:59]
	s_waitcnt lgkmcnt(0)
	v_mul_f32_e32 v52, v4, v156
	v_mul_f32_e32 v53, v5, v157
	v_cvt_pk_bf16_f32 v52, v52, v53
	s_nop 0
	v_lshl_add_u64 v[58:59], v[50:51], 0, v[58:59]
	s_waitcnt lgkmcnt(0)
	v_mul_f32_e32 v53, v6, v158
	v_mul_f32_e32 v54, v7, v159
	v_cvt_pk_bf16_f32 v53, v53, v54
	s_nop 0
	s_waitcnt lgkmcnt(0)
	v_mul_f32_e32 v54, v0, v160
	v_mul_f32_e32 v55, v1, v161
	v_cvt_pk_bf16_f32 v54, v54, v55
	s_nop 0
	s_waitcnt lgkmcnt(0)
	v_mul_f32_e32 v55, v2, v162
	v_mul_f32_e32 v56, v3, v163
	v_cvt_pk_bf16_f32 v55, v55, v56
	s_nop 0
	global_store_dwordx4 v[58:59], v[52:55], off
	v_or_b32_e32 v58, s0, v82
	v_ashrrev_i32_e32 v59, 31, v58
	v_lshlrev_b64 v[58:59], 12, v[58:59]
	s_waitcnt lgkmcnt(0)
	v_mul_f32_e32 v52, v4, v164
	v_mul_f32_e32 v53, v5, v165
	v_cvt_pk_bf16_f32 v52, v52, v53
	s_nop 0
	v_lshl_add_u64 v[58:59], v[50:51], 0, v[58:59]
	s_waitcnt lgkmcnt(0)
	v_mul_f32_e32 v53, v6, v166
	v_mul_f32_e32 v54, v7, v167
	v_cvt_pk_bf16_f32 v53, v53, v54
	s_nop 0
	s_waitcnt lgkmcnt(0)
	v_mul_f32_e32 v54, v0, v168
	v_mul_f32_e32 v55, v1, v169
	v_cvt_pk_bf16_f32 v54, v54, v55
	s_nop 0
	s_waitcnt lgkmcnt(0)
	v_mul_f32_e32 v55, v2, v170
	v_mul_f32_e32 v56, v3, v171
	v_cvt_pk_bf16_f32 v55, v55, v56
	s_nop 0
	global_store_dwordx4 v[58:59], v[52:55], off
	v_or_b32_e32 v58, s0, v83
	v_ashrrev_i32_e32 v59, 31, v58
	v_lshlrev_b64 v[58:59], 12, v[58:59]
	s_waitcnt lgkmcnt(0)
	v_mul_f32_e32 v52, v4, v172
	v_mul_f32_e32 v53, v5, v173
	v_cvt_pk_bf16_f32 v52, v52, v53
	s_nop 0
	v_lshl_add_u64 v[58:59], v[50:51], 0, v[58:59]
	s_waitcnt lgkmcnt(0)
	v_mul_f32_e32 v53, v6, v174
	v_mul_f32_e32 v54, v7, v175
	v_cvt_pk_bf16_f32 v53, v53, v54
	s_nop 0
	s_waitcnt lgkmcnt(0)
	v_mul_f32_e32 v54, v0, v176
	v_mul_f32_e32 v55, v1, v177
	v_cvt_pk_bf16_f32 v54, v54, v55
	s_nop 0
	s_waitcnt lgkmcnt(0)
	v_mul_f32_e32 v55, v2, v178
	v_mul_f32_e32 v56, v3, v179
	v_cvt_pk_bf16_f32 v55, v55, v56
	s_nop 0
	global_store_dwordx4 v[58:59], v[52:55], off
	v_or_b32_e32 v58, s0, v84
	v_ashrrev_i32_e32 v59, 31, v58
	v_lshlrev_b64 v[58:59], 12, v[58:59]
	s_waitcnt lgkmcnt(0)
	v_mul_f32_e32 v52, v4, v180
	v_mul_f32_e32 v53, v5, v181
	v_cvt_pk_bf16_f32 v52, v52, v53
	s_nop 0
	v_lshl_add_u64 v[58:59], v[50:51], 0, v[58:59]
	s_waitcnt lgkmcnt(0)
	v_mul_f32_e32 v53, v6, v182
	v_mul_f32_e32 v54, v7, v183
	v_cvt_pk_bf16_f32 v53, v53, v54
	s_nop 0
	s_waitcnt lgkmcnt(0)
	v_mul_f32_e32 v54, v0, v184
	v_mul_f32_e32 v55, v1, v185
	v_cvt_pk_bf16_f32 v54, v54, v55
	s_nop 0
	s_waitcnt lgkmcnt(0)
	v_mul_f32_e32 v55, v2, v186
	v_mul_f32_e32 v56, v3, v187
	v_cvt_pk_bf16_f32 v55, v55, v56
	s_nop 0
	global_store_dwordx4 v[58:59], v[52:55], off
	v_or_b32_e32 v58, s0, v85
	v_ashrrev_i32_e32 v59, 31, v58
	v_lshlrev_b64 v[58:59], 12, v[58:59]
	s_waitcnt lgkmcnt(0)
	v_mul_f32_e32 v52, v4, v188
	v_mul_f32_e32 v53, v5, v189
	v_cvt_pk_bf16_f32 v52, v52, v53
	s_nop 0
	v_lshl_add_u64 v[58:59], v[50:51], 0, v[58:59]
	s_waitcnt lgkmcnt(0)
	v_mul_f32_e32 v53, v6, v190
	v_mul_f32_e32 v54, v7, v191
	v_cvt_pk_bf16_f32 v53, v53, v54
	s_nop 0
	s_waitcnt lgkmcnt(0)
	v_mul_f32_e32 v54, v0, v192
	v_mul_f32_e32 v55, v1, v193
	v_cvt_pk_bf16_f32 v54, v54, v55
	s_nop 0
	s_waitcnt lgkmcnt(0)
	v_mul_f32_e32 v55, v2, v194
	v_mul_f32_e32 v56, v3, v195
	v_cvt_pk_bf16_f32 v55, v55, v56
	s_nop 0
	global_store_dwordx4 v[58:59], v[52:55], off
	v_or_b32_e32 v58, s0, v86
	v_ashrrev_i32_e32 v59, 31, v58
	v_lshlrev_b64 v[58:59], 12, v[58:59]
	s_waitcnt lgkmcnt(0)
	v_mul_f32_e32 v52, v4, v196
	v_mul_f32_e32 v53, v5, v197
	v_cvt_pk_bf16_f32 v52, v52, v53
	s_nop 0
	v_lshl_add_u64 v[58:59], v[50:51], 0, v[58:59]
	s_waitcnt lgkmcnt(0)
	v_mul_f32_e32 v53, v6, v198
	v_mul_f32_e32 v54, v7, v199
	v_cvt_pk_bf16_f32 v53, v53, v54
	s_nop 0
	s_waitcnt lgkmcnt(0)
	v_mul_f32_e32 v54, v0, v210
	v_mul_f32_e32 v55, v1, v211
	v_cvt_pk_bf16_f32 v54, v54, v55
	s_nop 0
	s_waitcnt lgkmcnt(0)
	v_mul_f32_e32 v55, v2, v212
	v_mul_f32_e32 v56, v3, v213
	v_cvt_pk_bf16_f32 v55, v55, v56
	s_nop 0
	global_store_dwordx4 v[58:59], v[52:55], off
	s_waitcnt lgkmcnt(0)
	v_mul_f32_e32 v4, v4, v214
	v_mul_f32_e32 v5, v5, v215
	v_cvt_pk_bf16_f32 v4, v4, v5
	s_nop 0
	s_waitcnt lgkmcnt(0)
	v_mul_f32_e32 v5, v6, v216
	v_mul_f32_e32 v6, v7, v217
	v_cvt_pk_bf16_f32 v5, v5, v6
	s_nop 0
	v_or_b32_e32 v52, s0, v87
	v_ashrrev_i32_e32 v53, 31, v52
	v_lshlrev_b64 v[52:53], 12, v[52:53]
	s_waitcnt lgkmcnt(0)
	v_mul_f32_e32 v0, v0, v218
	v_mul_f32_e32 v1, v1, v219
	v_cvt_pk_bf16_f32 v6, v0, v1
	s_nop 0
	s_waitcnt lgkmcnt(0)
	v_mul_f32_e32 v0, v2, v220
	v_mul_f32_e32 v1, v3, v221
	v_cvt_pk_bf16_f32 v7, v0, v1
	v_lshl_add_u64 v[0:1], v[50:51], 0, v[52:53]
	global_store_dwordx4 v[0:1], v[4:7], off
	s_waitcnt lgkmcnt(0)

.LBB0_444:
	v_add_u32_e32 v222, 0x400, v80
	ds_read2_b32 v[148:149], v80 offset1:65
	ds_read2_b32 v[150:151], v80 offset0:130 offset1:195
	ds_read2_b32 v[152:153], v222 offset0:4 offset1:69
	ds_read2_b32 v[154:155], v222 offset0:134 offset1:199
	ds_read2_b32 v[156:157], v80 offset0:8 offset1:73
	ds_read2_b32 v[158:159], v80 offset0:138 offset1:203
	ds_read2_b32 v[160:161], v222 offset0:12 offset1:77
	ds_read2_b32 v[162:163], v222 offset0:142 offset1:207
	ds_read2_b32 v[164:165], v80 offset0:16 offset1:81
	ds_read2_b32 v[166:167], v80 offset0:146 offset1:211
	ds_read2_b32 v[168:169], v222 offset0:20 offset1:85
	ds_read2_b32 v[170:171], v222 offset0:150 offset1:215
	ds_read2_b32 v[172:173], v80 offset0:24 offset1:89
	ds_read2_b32 v[174:175], v80 offset0:154 offset1:219
	ds_read2_b32 v[176:177], v222 offset0:28 offset1:93
	ds_read2_b32 v[178:179], v222 offset0:158 offset1:223
	ds_read2_b32 v[180:181], v80 offset0:32 offset1:97
	ds_read2_b32 v[182:183], v80 offset0:162 offset1:227
	ds_read2_b32 v[184:185], v222 offset0:36 offset1:101
	ds_read2_b32 v[186:187], v222 offset0:166 offset1:231
	ds_read2_b32 v[188:189], v80 offset0:40 offset1:105
	ds_read2_b32 v[190:191], v80 offset0:170 offset1:235
	ds_read2_b32 v[192:193], v222 offset0:44 offset1:109
	ds_read2_b32 v[194:195], v222 offset0:174 offset1:239
	ds_read2_b32 v[196:197], v80 offset0:48 offset1:113
	ds_read2_b32 v[198:199], v80 offset0:178 offset1:243
	ds_read2_b32 v[210:211], v222 offset0:52 offset1:117
	ds_read2_b32 v[212:213], v222 offset0:182 offset1:247
	ds_read2_b32 v[214:215], v80 offset0:56 offset1:121
	ds_read2_b32 v[216:217], v80 offset0:186 offset1:251
	ds_read2_b32 v[218:219], v222 offset0:60 offset1:125
	ds_read2_b32 v[220:221], v222 offset0:190 offset1:255
	s_nop 0
	s_mulk_i32 s6, 0xd400
	s_and_b32 s4, s4, 64
	s_waitcnt vmcnt(1) lgkmcnt(0)
	v_mul_f32_e32 v29, v4, v148
	v_mul_f32_e32 v50, v5, v149
	v_cvt_pk_bf16_f32 v52, v29, v50
	s_nop 0
	v_add_u32_e32 v29, 0x400, v80
	s_waitcnt lgkmcnt(0)
	v_mul_f32_e32 v50, v6, v150
	v_mul_f32_e32 v51, v7, v151
	v_cvt_pk_bf16_f32 v53, v50, v51
	s_nop 0
	v_lshl_add_u64 v[50:51], s[0:1], 1, v[46:47]
	s_add_i32 s0, s60, s6
	s_and_b32 s0, s0, 0xffffff00
	s_or_b32 s0, s4, s0
	s_waitcnt vmcnt(0) lgkmcnt(0)
	v_mul_f32_e32 v54, v0, v152
	v_mul_f32_e32 v55, v1, v153
	v_cvt_pk_bf16_f32 v54, v54, v55
	s_nop 0
	v_or_b32_e32 v58, s0, v79
	v_ashrrev_i32_e32 v59, 31, v58
	v_lshlrev_b64 v[58:59], 12, v[58:59]
	v_lshl_add_u64 v[58:59], v[50:51], 0, v[58:59]
	s_waitcnt lgkmcnt(0)
	v_mul_f32_e32 v55, v2, v154
	v_mul_f32_e32 v56, v3, v155
	v_cvt_pk_bf16_f32 v55, v55, v56
	s_nop 0
	global_store_dwordx4 v[58:59], v[52:55], off
	v_or_b32_e32 v58, s0, v81
	v_ashrrev_i32_e32 v59, 31, v58
	v_lshlrev_b64 v[58:59], 12, v[58:59]
	s_waitcnt lgkmcnt(0)
	v_mul_f32_e32 v52, v4, v156
	v_mul_f32_e32 v53, v5, v157
	v_cvt_pk_bf16_f32 v52, v52, v53
	s_nop 0
	v_lshl_add_u64 v[58:59], v[50:51], 0, v[58:59]
	s_waitcnt lgkmcnt(0)
	v_mul_f32_e32 v53, v6, v158
	v_mul_f32_e32 v54, v7, v159
	v_cvt_pk_bf16_f32 v53, v53, v54
	s_nop 0
	s_waitcnt lgkmcnt(0)
	v_mul_f32_e32 v54, v0, v160
	v_mul_f32_e32 v55, v1, v161
	v_cvt_pk_bf16_f32 v54, v54, v55
	s_nop 0
	s_waitcnt lgkmcnt(0)
	v_mul_f32_e32 v55, v2, v162
	v_mul_f32_e32 v56, v3, v163
	v_cvt_pk_bf16_f32 v55, v55, v56
	s_nop 0
	global_store_dwordx4 v[58:59], v[52:55], off
	v_or_b32_e32 v58, s0, v82
	v_ashrrev_i32_e32 v59, 31, v58
	v_lshlrev_b64 v[58:59], 12, v[58:59]
	s_waitcnt lgkmcnt(0)
	v_mul_f32_e32 v52, v4, v164
	v_mul_f32_e32 v53, v5, v165
	v_cvt_pk_bf16_f32 v52, v52, v53
	s_nop 0
	v_lshl_add_u64 v[58:59], v[50:51], 0, v[58:59]
	s_waitcnt lgkmcnt(0)
	v_mul_f32_e32 v53, v6, v166
	v_mul_f32_e32 v54, v7, v167
	v_cvt_pk_bf16_f32 v53, v53, v54
	s_nop 0
	s_waitcnt lgkmcnt(0)
	v_mul_f32_e32 v54, v0, v168
	v_mul_f32_e32 v55, v1, v169
	v_cvt_pk_bf16_f32 v54, v54, v55
	s_nop 0
	s_waitcnt lgkmcnt(0)
	v_mul_f32_e32 v55, v2, v170
	v_mul_f32_e32 v56, v3, v171
	v_cvt_pk_bf16_f32 v55, v55, v56
	s_nop 0
	global_store_dwordx4 v[58:59], v[52:55], off
	v_or_b32_e32 v58, s0, v83
	v_ashrrev_i32_e32 v59, 31, v58
	v_lshlrev_b64 v[58:59], 12, v[58:59]
	s_waitcnt lgkmcnt(0)
	v_mul_f32_e32 v52, v4, v172
	v_mul_f32_e32 v53, v5, v173
	v_cvt_pk_bf16_f32 v52, v52, v53
	s_nop 0
	v_lshl_add_u64 v[58:59], v[50:51], 0, v[58:59]
	s_waitcnt lgkmcnt(0)
	v_mul_f32_e32 v53, v6, v174
	v_mul_f32_e32 v54, v7, v175
	v_cvt_pk_bf16_f32 v53, v53, v54
	s_nop 0
	s_waitcnt lgkmcnt(0)
	v_mul_f32_e32 v54, v0, v176
	v_mul_f32_e32 v55, v1, v177
	v_cvt_pk_bf16_f32 v54, v54, v55
	s_nop 0
	s_waitcnt lgkmcnt(0)
	v_mul_f32_e32 v55, v2, v178
	v_mul_f32_e32 v56, v3, v179
	v_cvt_pk_bf16_f32 v55, v55, v56
	s_nop 0
	global_store_dwordx4 v[58:59], v[52:55], off
	v_or_b32_e32 v58, s0, v84
	v_ashrrev_i32_e32 v59, 31, v58
	v_lshlrev_b64 v[58:59], 12, v[58:59]
	s_waitcnt lgkmcnt(0)
	v_mul_f32_e32 v52, v4, v180
	v_mul_f32_e32 v53, v5, v181
	v_cvt_pk_bf16_f32 v52, v52, v53
	s_nop 0
	v_lshl_add_u64 v[58:59], v[50:51], 0, v[58:59]
	s_waitcnt lgkmcnt(0)
	v_mul_f32_e32 v53, v6, v182
	v_mul_f32_e32 v54, v7, v183
	v_cvt_pk_bf16_f32 v53, v53, v54
	s_nop 0
	s_waitcnt lgkmcnt(0)
	v_mul_f32_e32 v54, v0, v184
	v_mul_f32_e32 v55, v1, v185
	v_cvt_pk_bf16_f32 v54, v54, v55
	s_nop 0
	s_waitcnt lgkmcnt(0)
	v_mul_f32_e32 v55, v2, v186
	v_mul_f32_e32 v56, v3, v187
	v_cvt_pk_bf16_f32 v55, v55, v56
	s_nop 0
	global_store_dwordx4 v[58:59], v[52:55], off
	v_or_b32_e32 v58, s0, v85
	v_ashrrev_i32_e32 v59, 31, v58
	v_lshlrev_b64 v[58:59], 12, v[58:59]
	s_waitcnt lgkmcnt(0)
	v_mul_f32_e32 v52, v4, v188
	v_mul_f32_e32 v53, v5, v189
	v_cvt_pk_bf16_f32 v52, v52, v53
	s_nop 0
	v_lshl_add_u64 v[58:59], v[50:51], 0, v[58:59]
	s_waitcnt lgkmcnt(0)
	v_mul_f32_e32 v53, v6, v190
	v_mul_f32_e32 v54, v7, v191
	v_cvt_pk_bf16_f32 v53, v53, v54
	s_nop 0
	s_waitcnt lgkmcnt(0)
	v_mul_f32_e32 v54, v0, v192
	v_mul_f32_e32 v55, v1, v193
	v_cvt_pk_bf16_f32 v54, v54, v55
	s_nop 0
	s_waitcnt lgkmcnt(0)
	v_mul_f32_e32 v55, v2, v194
	v_mul_f32_e32 v56, v3, v195
	v_cvt_pk_bf16_f32 v55, v55, v56
	s_nop 0
	global_store_dwordx4 v[58:59], v[52:55], off
	v_or_b32_e32 v58, s0, v86
	v_ashrrev_i32_e32 v59, 31, v58
	v_lshlrev_b64 v[58:59], 12, v[58:59]
	s_waitcnt lgkmcnt(0)
	v_mul_f32_e32 v52, v4, v196
	v_mul_f32_e32 v53, v5, v197
	v_cvt_pk_bf16_f32 v52, v52, v53
	s_nop 0
	v_lshl_add_u64 v[58:59], v[50:51], 0, v[58:59]
	s_waitcnt lgkmcnt(0)
	v_mul_f32_e32 v53, v6, v198
	v_mul_f32_e32 v54, v7, v199
	v_cvt_pk_bf16_f32 v53, v53, v54
	s_nop 0
	s_waitcnt lgkmcnt(0)
	v_mul_f32_e32 v54, v0, v210
	v_mul_f32_e32 v55, v1, v211
	v_cvt_pk_bf16_f32 v54, v54, v55
	s_nop 0
	s_waitcnt lgkmcnt(0)
	v_mul_f32_e32 v55, v2, v212
	v_mul_f32_e32 v56, v3, v213
	v_cvt_pk_bf16_f32 v55, v55, v56
	s_nop 0
	global_store_dwordx4 v[58:59], v[52:55], off
	s_waitcnt lgkmcnt(0)
	v_mul_f32_e32 v4, v4, v214
	v_mul_f32_e32 v5, v5, v215
	v_cvt_pk_bf16_f32 v4, v4, v5
	s_nop 0
	s_waitcnt lgkmcnt(0)
	v_mul_f32_e32 v5, v6, v216
	v_mul_f32_e32 v6, v7, v217
	v_cvt_pk_bf16_f32 v5, v5, v6
	s_nop 0
	v_or_b32_e32 v52, s0, v87
	v_ashrrev_i32_e32 v53, 31, v52
	v_lshlrev_b64 v[52:53], 12, v[52:53]
	s_waitcnt lgkmcnt(0)
	v_mul_f32_e32 v0, v0, v218
	v_mul_f32_e32 v1, v1, v219
	v_cvt_pk_bf16_f32 v6, v0, v1
	s_nop 0
	s_waitcnt lgkmcnt(0)
	v_mul_f32_e32 v0, v2, v220
	v_mul_f32_e32 v1, v3, v221
	v_cvt_pk_bf16_f32 v7, v0, v1
	v_lshl_add_u64 v[0:1], v[50:51], 0, v[52:53]
	global_store_dwordx4 v[0:1], v[4:7], off
	s_waitcnt lgkmcnt(0)

.LBB0_446:
	s_andn2_b64 vcc, exec, s[0:1]
	s_cbranch_vccnz .LBB0_448
	s_load_dwordx2 s[0:1], s[30:31], 0x38
	v_lshlrev_b32_e32 v204, 2, v8
	v_add_u32_e32 v29, 0x410, v78
	s_waitcnt lgkmcnt(0)
	s_add_u32 s5, s0, s42
	s_addc_u32 s25, s1, s43
	s_ashr_i32 s0, s49, 31
	s_lshr_b32 s0, s0, 27
	s_add_i32 s0, s49, s0
	s_ashr_i32 s0, s0, 5
	s_lshl_b32 s1, s0, 11
	s_lshl_b32 s4, s0, 6
	s_sub_i32 s0, s22, s1
	s_ashr_i32 s1, s0, 31
	v_or_b32_e32 v112, s4, v11
	s_lshl_b64 s[6:7], s[0:1], 2
	s_add_u32 s6, s5, s6
	v_or_b32_e32 v2, 4, v112
	s_addc_u32 s7, s25, s7
	v_ashrrev_i32_e32 v113, 31, v112
	v_ashrrev_i32_e32 v3, 31, v2
	v_lshl_add_u64 v[114:115], s[6:7], 0, v[204:205]
	v_lshlrev_b64 v[0:1], 13, v[112:113]
	v_lshlrev_b64 v[2:3], 13, v[2:3]
	v_lshl_add_u64 v[0:1], v[114:115], 0, v[0:1]
	v_lshl_add_u64 v[4:5], v[114:115], 0, v[2:3]
	v_or_b32_e32 v50, 8, v112
	v_or_b32_e32 v52, 12, v112
	global_load_dwordx4 v[0:3], v[0:1], off
	s_nop 0
	global_load_dwordx4 v[4:7], v[4:5], off
	v_ashrrev_i32_e32 v51, 31, v50
	v_ashrrev_i32_e32 v53, 31, v52
	v_lshlrev_b64 v[50:51], 13, v[50:51]
	v_lshlrev_b64 v[52:53], 13, v[52:53]
	v_lshl_add_u64 v[50:51], v[114:115], 0, v[50:51]
	v_lshl_add_u64 v[54:55], v[114:115], 0, v[52:53]
	global_load_dwordx4 v[50:53], v[50:51], off
	s_nop 0
	global_load_dwordx4 v[54:57], v[54:55], off
	v_or_b32_e32 v58, 16, v112
	v_or_b32_e32 v60, 20, v112
	v_ashrrev_i32_e32 v59, 31, v58
	v_ashrrev_i32_e32 v61, 31, v60
	v_lshlrev_b64 v[58:59], 13, v[58:59]
	v_lshlrev_b64 v[60:61], 13, v[60:61]
	v_lshl_add_u64 v[58:59], v[114:115], 0, v[58:59]
	v_lshl_add_u64 v[62:63], v[114:115], 0, v[60:61]
	global_load_dwordx4 v[58:61], v[58:59], off
	s_nop 0
	global_load_dwordx4 v[62:65], v[62:63], off
	v_or_b32_e32 v66, 24, v112
	v_or_b32_e32 v68, 28, v112
	v_ashrrev_i32_e32 v67, 31, v66
	v_ashrrev_i32_e32 v69, 31, v68
	v_lshlrev_b64 v[66:67], 13, v[66:67]
	v_lshlrev_b64 v[68:69], 13, v[68:69]
	v_lshl_add_u64 v[66:67], v[114:115], 0, v[66:67]
	v_lshl_add_u64 v[70:71], v[114:115], 0, v[68:69]
	global_load_dwordx4 v[66:69], v[66:67], off
	s_nop 0
	global_load_dwordx4 v[70:73], v[70:71], off
	v_or_b32_e32 v74, 32, v112
	v_or_b32_e32 v76, 36, v112
	v_ashrrev_i32_e32 v75, 31, v74
	v_ashrrev_i32_e32 v77, 31, v76
	v_lshlrev_b64 v[74:75], 13, v[74:75]
	v_lshlrev_b64 v[76:77], 13, v[76:77]
	v_lshl_add_u64 v[74:75], v[114:115], 0, v[74:75]
	v_lshl_add_u64 v[88:89], v[114:115], 0, v[76:77]
	global_load_dwordx4 v[74:77], v[74:75], off
	s_nop 0
	global_load_dwordx4 v[88:91], v[88:89], off
	v_or_b32_e32 v92, 40, v112
	v_or_b32_e32 v94, 44, v112
	v_ashrrev_i32_e32 v93, 31, v92
	v_ashrrev_i32_e32 v95, 31, v94
	v_lshlrev_b64 v[92:93], 13, v[92:93]
	v_lshlrev_b64 v[94:95], 13, v[94:95]
	v_lshl_add_u64 v[92:93], v[114:115], 0, v[92:93]
	v_lshl_add_u64 v[96:97], v[114:115], 0, v[94:95]
	v_or_b32_e32 v100, 48, v112
	global_load_dwordx4 v[92:95], v[92:93], off
	s_nop 0
	global_load_dwordx4 v[96:99], v[96:97], off
	v_ashrrev_i32_e32 v101, 31, v100
	v_lshlrev_b64 v[100:101], 13, v[100:101]
	v_or_b32_e32 v104, 52, v112
	v_lshl_add_u64 v[100:101], v[114:115], 0, v[100:101]
	v_ashrrev_i32_e32 v105, 31, v104
	global_load_dwordx4 v[100:103], v[100:101], off
	v_lshlrev_b64 v[104:105], 13, v[104:105]
	v_or_b32_e32 v108, 56, v112
	v_lshl_add_u64 v[104:105], v[114:115], 0, v[104:105]
	v_ashrrev_i32_e32 v109, 31, v108
	global_load_dwordx4 v[104:107], v[104:105], off
	v_lshlrev_b64 v[108:109], 13, v[108:109]
	v_or_b32_e32 v112, 60, v112
	v_lshl_add_u64 v[108:109], v[114:115], 0, v[108:109]
	v_ashrrev_i32_e32 v113, 31, v112
	global_load_dwordx4 v[108:111], v[108:109], off
	v_lshlrev_b64 v[112:113], 13, v[112:113]
	v_lshl_add_u64 v[112:113], v[114:115], 0, v[112:113]
	global_load_dwordx4 v[112:115], v[112:113], off
	s_ashr_i32 s5, s4, 31
	s_waitcnt vmcnt(0)
	ds_write2_b32 v78, v0, v1 offset1:1
	ds_write2_b32 v78, v2, v3 offset0:2 offset1:3
	ds_write2_b32 v29, v4, v5 offset1:1
	v_add_u32_e32 v0, 0x418, v78
	ds_write2_b32 v0, v6, v7 offset1:1
	v_add_u32_e32 v0, 0x820, v78
	v_add_u32_e32 v29, 0x400, v80
	v_lshl_add_u64 v[6:7], s[4:5], 1, v[38:39]
	ds_write2_b32 v0, v50, v51 offset1:1
	v_add_u32_e32 v0, 0x828, v78
	ds_write2_b32 v0, v52, v53 offset1:1
	v_add_u32_e32 v0, 0xc30, v78
	ds_write2_b32 v0, v54, v55 offset1:1
	v_add_u32_e32 v0, 0xc38, v78
	ds_write2_b32 v0, v56, v57 offset1:1
	v_add_u32_e32 v0, 0x1040, v78
	ds_write2_b32 v0, v58, v59 offset1:1
	v_add_u32_e32 v0, 0x1048, v78
	ds_write2_b32 v0, v60, v61 offset1:1
	v_add_u32_e32 v0, 0x1450, v78
	ds_write2_b32 v0, v62, v63 offset1:1
	v_add_u32_e32 v0, 0x1458, v78
	ds_write2_b32 v0, v64, v65 offset1:1
	v_add_u32_e32 v0, 0x1860, v78
	ds_write2_b32 v0, v66, v67 offset1:1
	v_add_u32_e32 v0, 0x1868, v78
	ds_write2_b32 v0, v68, v69 offset1:1
	v_add_u32_e32 v0, 0x1c70, v78
	ds_write2_b32 v0, v70, v71 offset1:1
	v_add_u32_e32 v0, 0x1c78, v78
	ds_write2_b32 v0, v72, v73 offset1:1
	v_add_u32_e32 v0, 0x2080, v78
	ds_write2_b32 v0, v74, v75 offset1:1
	v_add_u32_e32 v0, 0x2088, v78
	ds_write2_b32 v0, v76, v77 offset1:1
	v_add_u32_e32 v0, 0x2490, v78
	ds_write2_b32 v0, v88, v89 offset1:1
	v_add_u32_e32 v0, 0x2498, v78
	ds_write2_b32 v0, v90, v91 offset1:1
	v_add_u32_e32 v0, 0x28a0, v78
	ds_write2_b32 v0, v92, v93 offset1:1
	v_add_u32_e32 v0, 0x28a8, v78
	ds_write2_b32 v0, v94, v95 offset1:1
	v_add_u32_e32 v0, 0x2cb0, v78
	ds_write2_b32 v0, v96, v97 offset1:1
	v_add_u32_e32 v0, 0x2cb8, v78
	ds_write2_b32 v0, v98, v99 offset1:1
	v_add_u32_e32 v0, 0x30c0, v78
	ds_write2_b32 v0, v100, v101 offset1:1
	v_add_u32_e32 v0, 0x30c8, v78
	ds_write2_b32 v0, v102, v103 offset1:1
	v_add_u32_e32 v0, 0x34d0, v78
	ds_write2_b32 v0, v104, v105 offset1:1
	v_add_u32_e32 v0, 0x34d8, v78
	ds_write2_b32 v0, v106, v107 offset1:1
	v_add_u32_e32 v0, 0x38e0, v78
	ds_write2_b32 v0, v108, v109 offset1:1
	v_add_u32_e32 v0, 0x38e8, v78
	ds_write2_b32 v0, v110, v111 offset1:1
	v_add_u32_e32 v0, 0x3cf0, v78
	ds_write2_b32 v0, v112, v113 offset1:1
	v_add_u32_e32 v0, 0x3cf8, v78
	ds_write2_b32 v0, v114, v115 offset1:1
	s_waitcnt lgkmcnt(0)
	ds_read2_b32 v[148:149], v80 offset1:65
	ds_read2_b32 v[150:151], v80 offset0:130 offset1:195
	ds_read2_b32 v[152:153], v29 offset0:4 offset1:69
	ds_read2_b32 v[154:155], v29 offset0:134 offset1:199
	ds_read2_b32 v[156:157], v80 offset0:8 offset1:73
	ds_read2_b32 v[158:159], v80 offset0:138 offset1:203
	ds_read2_b32 v[160:161], v29 offset0:12 offset1:77
	ds_read2_b32 v[162:163], v29 offset0:142 offset1:207
	ds_read2_b32 v[164:165], v80 offset0:16 offset1:81
	ds_read2_b32 v[166:167], v80 offset0:146 offset1:211
	ds_read2_b32 v[168:169], v29 offset0:20 offset1:85
	ds_read2_b32 v[170:171], v29 offset0:150 offset1:215
	ds_read2_b32 v[172:173], v80 offset0:24 offset1:89
	ds_read2_b32 v[174:175], v80 offset0:154 offset1:219
	ds_read2_b32 v[176:177], v29 offset0:28 offset1:93
	ds_read2_b32 v[178:179], v29 offset0:158 offset1:223
	ds_read2_b32 v[180:181], v80 offset0:32 offset1:97
	ds_read2_b32 v[182:183], v80 offset0:162 offset1:227
	ds_read2_b32 v[184:185], v29 offset0:36 offset1:101
	ds_read2_b32 v[186:187], v29 offset0:166 offset1:231
	ds_read2_b32 v[188:189], v80 offset0:40 offset1:105
	ds_read2_b32 v[190:191], v80 offset0:170 offset1:235
	ds_read2_b32 v[192:193], v29 offset0:44 offset1:109
	ds_read2_b32 v[194:195], v29 offset0:174 offset1:239
	ds_read2_b32 v[196:197], v80 offset0:48 offset1:113
	ds_read2_b32 v[198:199], v80 offset0:178 offset1:243
	ds_read2_b32 v[210:211], v29 offset0:52 offset1:117
	ds_read2_b32 v[212:213], v29 offset0:182 offset1:247
	ds_read2_b32 v[214:215], v80 offset0:56 offset1:121
	ds_read2_b32 v[216:217], v80 offset0:186 offset1:251
	ds_read2_b32 v[218:219], v29 offset0:60 offset1:125
	ds_read2_b32 v[220:221], v29 offset0:190 offset1:255
	s_nop 0
	s_waitcnt lgkmcnt(0)
	v_cvt_pk_bf16_f32 v0, v148, v149
	s_nop 0
	s_waitcnt lgkmcnt(0)
	v_cvt_pk_bf16_f32 v1, v150, v151
	s_nop 0
	s_waitcnt lgkmcnt(0)
	v_cvt_pk_bf16_f32 v2, v152, v153
	s_nop 0
	s_waitcnt lgkmcnt(0)
	v_cvt_pk_bf16_f32 v3, v154, v155
	v_add_u32_e32 v4, s0, v79
	v_ashrrev_i32_e32 v5, 31, v4
	v_lshlrev_b64 v[52:53], 12, v[4:5]
	v_lshl_add_u64 v[52:53], v[6:7], 0, v[52:53]
	s_nop 0
	global_store_dwordx4 v[52:53], v[0:3], off
	s_waitcnt lgkmcnt(0)
	s_nop 0
	v_cvt_pk_bf16_f32 v0, v156, v157
	s_nop 0
	s_waitcnt lgkmcnt(0)
	v_cvt_pk_bf16_f32 v1, v158, v159
	s_nop 0
	s_waitcnt lgkmcnt(0)
	v_cvt_pk_bf16_f32 v2, v160, v161
	s_nop 0
	s_waitcnt lgkmcnt(0)
	v_cvt_pk_bf16_f32 v3, v162, v163
	v_add_u32_e32 v50, 8, v4
	v_ashrrev_i32_e32 v51, 31, v50
	v_lshlrev_b64 v[50:51], 12, v[50:51]
	v_lshl_add_u64 v[50:51], v[6:7], 0, v[50:51]
	s_nop 0
	global_store_dwordx4 v[50:51], v[0:3], off
	s_waitcnt lgkmcnt(0)
	s_nop 0
	v_cvt_pk_bf16_f32 v0, v164, v165
	s_nop 0
	s_waitcnt lgkmcnt(0)
	v_cvt_pk_bf16_f32 v1, v166, v167
	s_nop 0
	s_waitcnt lgkmcnt(0)
	v_cvt_pk_bf16_f32 v2, v168, v169
	s_nop 0
	s_waitcnt lgkmcnt(0)
	v_cvt_pk_bf16_f32 v3, v170, v171
	v_add_u32_e32 v50, 16, v4
	v_ashrrev_i32_e32 v51, 31, v50
	v_lshlrev_b64 v[50:51], 12, v[50:51]
	v_lshl_add_u64 v[50:51], v[6:7], 0, v[50:51]
	s_nop 0
	global_store_dwordx4 v[50:51], v[0:3], off
	s_waitcnt lgkmcnt(0)
	s_nop 0
	v_cvt_pk_bf16_f32 v0, v172, v173
	s_nop 0
	s_waitcnt lgkmcnt(0)
	v_cvt_pk_bf16_f32 v1, v174, v175
	s_nop 0
	s_waitcnt lgkmcnt(0)
	v_cvt_pk_bf16_f32 v2, v176, v177
	s_nop 0
	s_waitcnt lgkmcnt(0)
	v_cvt_pk_bf16_f32 v3, v178, v179
	v_add_u32_e32 v50, 24, v4
	v_ashrrev_i32_e32 v51, 31, v50
	v_lshlrev_b64 v[50:51], 12, v[50:51]
	v_lshl_add_u64 v[50:51], v[6:7], 0, v[50:51]
	s_nop 0
	global_store_dwordx4 v[50:51], v[0:3], off
	s_waitcnt lgkmcnt(0)
	s_nop 0
	v_cvt_pk_bf16_f32 v0, v180, v181
	s_nop 0
	s_waitcnt lgkmcnt(0)
	v_cvt_pk_bf16_f32 v1, v182, v183
	s_nop 0
	s_waitcnt lgkmcnt(0)
	v_cvt_pk_bf16_f32 v2, v184, v185
	s_nop 0
	s_waitcnt lgkmcnt(0)
	v_cvt_pk_bf16_f32 v3, v186, v187
	v_add_u32_e32 v50, 32, v4
	v_ashrrev_i32_e32 v51, 31, v50
	v_lshlrev_b64 v[50:51], 12, v[50:51]
	v_lshl_add_u64 v[50:51], v[6:7], 0, v[50:51]
	s_nop 0
	global_store_dwordx4 v[50:51], v[0:3], off
	s_waitcnt lgkmcnt(0)
	s_nop 0
	v_cvt_pk_bf16_f32 v0, v188, v189
	s_nop 0
	s_waitcnt lgkmcnt(0)
	v_cvt_pk_bf16_f32 v1, v190, v191
	s_nop 0
	s_waitcnt lgkmcnt(0)
	v_cvt_pk_bf16_f32 v2, v192, v193
	s_nop 0
	s_waitcnt lgkmcnt(0)
	v_cvt_pk_bf16_f32 v3, v194, v195
	v_add_u32_e32 v50, 40, v4
	v_ashrrev_i32_e32 v51, 31, v50
	v_lshlrev_b64 v[50:51], 12, v[50:51]
	v_lshl_add_u64 v[50:51], v[6:7], 0, v[50:51]
	s_nop 0
	global_store_dwordx4 v[50:51], v[0:3], off
	s_waitcnt lgkmcnt(0)
	s_nop 0
	v_cvt_pk_bf16_f32 v0, v196, v197
	s_nop 0
	s_waitcnt lgkmcnt(0)
	v_cvt_pk_bf16_f32 v1, v198, v199
	s_nop 0
	s_waitcnt lgkmcnt(0)
	v_cvt_pk_bf16_f32 v2, v210, v211
	s_nop 0
	s_waitcnt lgkmcnt(0)
	v_cvt_pk_bf16_f32 v3, v212, v213
	v_add_u32_e32 v50, 48, v4
	v_ashrrev_i32_e32 v51, 31, v50
	v_lshlrev_b64 v[50:51], 12, v[50:51]
	v_add_u32_e32 v4, 56, v4
	v_lshl_add_u64 v[50:51], v[6:7], 0, v[50:51]
	v_ashrrev_i32_e32 v5, 31, v4
	s_nop 0
	global_store_dwordx4 v[50:51], v[0:3], off
	v_lshlrev_b64 v[4:5], 12, v[4:5]
	v_lshl_add_u64 v[4:5], v[6:7], 0, v[4:5]
	s_waitcnt lgkmcnt(0)
	v_cvt_pk_bf16_f32 v0, v214, v215
	s_nop 0
	s_waitcnt lgkmcnt(0)
	v_cvt_pk_bf16_f32 v1, v216, v217
	s_nop 0
	s_waitcnt lgkmcnt(0)
	v_cvt_pk_bf16_f32 v2, v218, v219
	s_nop 0
	s_waitcnt lgkmcnt(0)
	v_cvt_pk_bf16_f32 v3, v220, v221
	global_store_dwordx4 v[4:5], v[0:3], off
	s_waitcnt lgkmcnt(0)
